# PLE gate epilogue hand-written: bias loads hoisted, xb/pp loads software-pipelined 7 blocks deep with counted vmcnt, packed f32 math
# speedup vs baseline: 1.0042x; 1.0028x over previous
; DI float bflo(unsigned w) { return __uint_as_float(w << 16); }
; DI float bfhi(unsigned w) { return __uint_as_float(w & 0xffff0000u); }
; DI unsigned cvt_pk_bf16(float lo, float hi) { unsigned r; asm volatile("v_cvt_pk_bf16_f32 %0, %1, %2" : "=v"(r) : "v"(lo), "v"(hi)); return r; }
; DI float sigmoidf_(float x) { return __builtin_amdgcn_rcpf(1.0f + __expf(-x)); }
;     DI void operator()(const f32x4 (&acc)[2][2][4][2], const pg8::Unit& u, int wr, int wc, int fr, int fq) const {
;         const int row0 = u.pm * 256 + wr * 64 + fr, col0 = u.pn * 256 + wc * 32 + 8 * fq;
; #pragma unroll
;         for (int ai = 0; ai < 2; ++ai)
; #pragma unroll
;             for (int m = 0; m < 4; ++m) {
;                 const size_t off = (size_t)(row0 + ai * 128 + m * 16) * D_ + col0;
; #pragma unroll
;                 for (int bj = 0; bj < 2; ++bj) {
;                     const size_t o = off + bj * 128;
;                     const f32x4 b0 = *(const f32x4*)(bg + col0 + bj * 128), b1 = *(const f32x4*)(bg + col0 + bj * 128 + 4);
;                     const u32x4 rb = *(const u32x4*)(xb + o);
;                     const u32x4 pb = *(const u32x4*)(pp + o);
;                     const f32x4 x0 = (f32x4){bflo(rb.x), bfhi(rb.x), bflo(rb.y), bfhi(rb.y)}, x1 = (f32x4){bflo(rb.z), bfhi(rb.z), bflo(rb.w), bfhi(rb.w)};
;                     const f32x4 p0 = (f32x4){bflo(pb.x), bfhi(pb.x), bflo(pb.y), bfhi(pb.y)}, p1 = (f32x4){bflo(pb.z), bfhi(pb.z), bflo(pb.w), bfhi(pb.w)};
;                     f32x4 v0, v1;
; #pragma unroll
;                     for (int j = 0; j < 4; ++j) { v0[j] = x0[j] + sigmoidf_(acc[ai][bj][m][0][j] + b0[j]) * p0[j]; v1[j] = x1[j] + sigmoidf_(acc[ai][bj][m][1][j] + b1[j]) * p1[j]; }
;                     if (out) { *(f32x4*)(out + o) = v0; *(f32x4*)(out + o + 4) = v1; }
;                     if (xbn) { u32x4 w; w.x = cvt_pk_bf16(v0[0], v0[1]); w.y = cvt_pk_bf16(v0[2], v0[3]); w.z = cvt_pk_bf16(v1[0], v1[1]); w.w = cvt_pk_bf16(v1[2], v1[3]); *(u32x4*)(xbn + o) = w; }
.LBB0_594:
	v_mov_b32_e32 v132, v163
	s_lshl_b32 s4, s26, 8
	s_add_i32 s4, s4, s54
	v_readlane_b32 s94, v255, 40
	v_readlane_b32 s95, v255, 41
	v_readlane_b32 s96, v255, 42
	v_readlane_b32 s97, v255, 43
	v_lshrrev_b32_e32 v128, 1, v132
	v_and_b32_e32 v128, 0x78, v128
	v_and_or_b32 v132, v132, 15, s4
	v_lshl_or_b32 v130, s34, 8, v128
	v_lshlrev_b32_e32 v244, 2, v130
	v_lshlrev_b32_e32 v245, 11, v132
	v_lshl_add_u32 v245, v130, 1, v245
	v_lshlrev_b32_e32 v238, 1, v245
	v_mov_b32_e32 v246, 0xbfb8aa3b
	v_mov_b32_e32 v247, 0xbfb8aa3b
	v_mov_b32_e32 v236, 1.0
	v_mov_b32_e32 v237, 1.0
	s_andn2_b64 vcc, exec, s[14:15]
	s_cbranch_vccnz .Lepp_bf16
	global_load_dwordx4 v[212:215], v244, s[8:9]
	global_load_dwordx4 v[216:219], v244, s[8:9] offset:16
	global_load_dwordx4 v[220:223], v244, s[8:9] offset:512
	global_load_dwordx4 v[224:227], v244, s[8:9] offset:528
	v_mov_b32_e32 v148, v245
	global_load_dwordx4 v[172:175], v148, s[94:95]
	global_load_dwordx4 v[176:179], v148, s[20:21]
	global_load_dwordx4 v[180:183], v148, s[94:95] offset:256
	global_load_dwordx4 v[184:187], v148, s[20:21] offset:256
	v_add_u32_e32 v149, 0x8000, v245
	global_load_dwordx4 v[188:191], v149, s[94:95]
	global_load_dwordx4 v[192:195], v149, s[20:21]
	global_load_dwordx4 v[196:199], v149, s[94:95] offset:256
	global_load_dwordx4 v[200:203], v149, s[20:21] offset:256
	v_add_u32_e32 v148, 0x10000, v245
	global_load_dwordx4 v[204:207], v148, s[94:95]
	global_load_dwordx4 v[208:211], v148, s[20:21]
	global_load_dwordx4 v[228:231], v148, s[94:95] offset:256
	global_load_dwordx4 v[232:235], v148, s[20:21] offset:256
	v_add_u32_e32 v149, 0x18000, v245
	global_load_dwordx4 v[128:131], v149, s[94:95]
	global_load_dwordx4 v[132:135], v149, s[20:21]
	s_waitcnt vmcnt(14)
	v_pk_add_f32 v[124:125], v[124:125], v[212:213]
	v_pk_add_f32 v[126:127], v[126:127], v[214:215]
	v_pk_add_f32 v[120:121], v[120:121], v[216:217]
	v_pk_add_f32 v[122:123], v[122:123], v[218:219]
	v_pk_mul_f32 v[124:125], v[124:125], v[246:247]
	v_pk_mul_f32 v[126:127], v[126:127], v[246:247]
	v_pk_mul_f32 v[120:121], v[120:121], v[246:247]
	v_pk_mul_f32 v[122:123], v[122:123], v[246:247]
	v_exp_f32_e32 v120, v120
	v_exp_f32_e32 v121, v121
	v_exp_f32_e32 v122, v122
	v_exp_f32_e32 v123, v123
	v_exp_f32_e32 v124, v124
	v_exp_f32_e32 v125, v125
	v_exp_f32_e32 v126, v126
	v_exp_f32_e32 v127, v127
	v_pk_add_f32 v[124:125], v[124:125], v[236:237]
	v_pk_add_f32 v[126:127], v[126:127], v[236:237]
	v_pk_add_f32 v[120:121], v[120:121], v[236:237]
	v_pk_add_f32 v[122:123], v[122:123], v[236:237]
	v_rcp_f32_e32 v120, v120
	v_rcp_f32_e32 v121, v121
	v_rcp_f32_e32 v122, v122
	v_rcp_f32_e32 v123, v123
	v_rcp_f32_e32 v124, v124
	v_rcp_f32_e32 v125, v125
	v_rcp_f32_e32 v126, v126
	v_rcp_f32_e32 v127, v127
	s_waitcnt vmcnt(12)
	v_lshlrev_b32_e32 v138, 16, v172
	v_and_b32_e32 v139, 0xffff0000, v172
	v_lshlrev_b32_e32 v140, 16, v173
	v_and_b32_e32 v141, 0xffff0000, v173
	v_lshlrev_b32_e32 v144, 16, v174
	v_and_b32_e32 v145, 0xffff0000, v174
	v_lshlrev_b32_e32 v146, 16, v175
	v_and_b32_e32 v147, 0xffff0000, v175
	v_lshlrev_b32_e32 v154, 16, v176
	v_and_b32_e32 v155, 0xffff0000, v176
	v_lshlrev_b32_e32 v156, 16, v177
	v_and_b32_e32 v157, 0xffff0000, v177
	v_lshlrev_b32_e32 v158, 16, v178
	v_and_b32_e32 v159, 0xffff0000, v178
	v_lshlrev_b32_e32 v160, 16, v179
	v_and_b32_e32 v161, 0xffff0000, v179
	v_pk_fma_f32 v[124:125], v[124:125], v[154:155], v[138:139]
	v_pk_fma_f32 v[126:127], v[126:127], v[156:157], v[140:141]
	v_pk_fma_f32 v[120:121], v[120:121], v[158:159], v[144:145]
	v_pk_fma_f32 v[122:123], v[122:123], v[160:161], v[146:147]
	v_mov_b32_e32 v169, v238
	global_store_dwordx4 v169, v[124:127], s[10:11]
	global_store_dwordx4 v169, v[120:123], s[10:11] offset:16
	global_load_dwordx4 v[172:175], v149, s[94:95] offset:256
	global_load_dwordx4 v[176:179], v149, s[20:21] offset:256
	v_pk_add_f32 v[116:117], v[116:117], v[220:221]
	v_pk_add_f32 v[118:119], v[118:119], v[222:223]
	v_pk_add_f32 v[112:113], v[112:113], v[224:225]
	v_pk_add_f32 v[114:115], v[114:115], v[226:227]
	v_pk_mul_f32 v[116:117], v[116:117], v[246:247]
	v_pk_mul_f32 v[118:119], v[118:119], v[246:247]
	v_pk_mul_f32 v[112:113], v[112:113], v[246:247]
	v_pk_mul_f32 v[114:115], v[114:115], v[246:247]
	v_exp_f32_e32 v112, v112
	v_exp_f32_e32 v113, v113
	v_exp_f32_e32 v114, v114
	v_exp_f32_e32 v115, v115
	v_exp_f32_e32 v116, v116
	v_exp_f32_e32 v117, v117
	v_exp_f32_e32 v118, v118
	v_exp_f32_e32 v119, v119
	v_pk_add_f32 v[116:117], v[116:117], v[236:237]
	v_pk_add_f32 v[118:119], v[118:119], v[236:237]
	v_pk_add_f32 v[112:113], v[112:113], v[236:237]
	v_pk_add_f32 v[114:115], v[114:115], v[236:237]
	v_rcp_f32_e32 v112, v112
	v_rcp_f32_e32 v113, v113
	v_rcp_f32_e32 v114, v114
	v_rcp_f32_e32 v115, v115
	v_rcp_f32_e32 v116, v116
	v_rcp_f32_e32 v117, v117
	v_rcp_f32_e32 v118, v118
	v_rcp_f32_e32 v119, v119
	s_waitcnt vmcnt(14)
; DI float bflo(unsigned w) { return __uint_as_float(w << 16); }
; DI float bfhi(unsigned w) { return __uint_as_float(w & 0xffff0000u); }
; DI unsigned cvt_pk_bf16(float lo, float hi) { unsigned r; asm volatile("v_cvt_pk_bf16_f32 %0, %1, %2" : "=v"(r) : "v"(lo), "v"(hi)); return r; }
; DI float sigmoidf_(float x) { return __builtin_amdgcn_rcpf(1.0f + __expf(-x)); }
;     DI void operator()(const f32x4 (&acc)[2][2][4][2], const pg8::Unit& u, int wr, int wc, int fr, int fq) const {
;         const int row0 = u.pm * 256 + wr * 64 + fr, col0 = u.pn * 256 + wc * 32 + 8 * fq;
; #pragma unroll
;         for (int ai = 0; ai < 2; ++ai)
; #pragma unroll
;             for (int m = 0; m < 4; ++m) {
;                 const size_t off = (size_t)(row0 + ai * 128 + m * 16) * D_ + col0;
; #pragma unroll
;                 for (int bj = 0; bj < 2; ++bj) {
;                     const size_t o = off + bj * 128;
;                     const f32x4 b0 = *(const f32x4*)(bg + col0 + bj * 128), b1 = *(const f32x4*)(bg + col0 + bj * 128 + 4);
;                     const u32x4 rb = *(const u32x4*)(xb + o);
;                     const u32x4 pb = *(const u32x4*)(pp + o);
;                     const f32x4 x0 = (f32x4){bflo(rb.x), bfhi(rb.x), bflo(rb.y), bfhi(rb.y)}, x1 = (f32x4){bflo(rb.z), bfhi(rb.z), bflo(rb.w), bfhi(rb.w)};
;                     const f32x4 p0 = (f32x4){bflo(pb.x), bfhi(pb.x), bflo(pb.y), bfhi(pb.y)}, p1 = (f32x4){bflo(pb.z), bfhi(pb.z), bflo(pb.w), bfhi(pb.w)};
;                     f32x4 v0, v1;
; #pragma unroll
;                     for (int j = 0; j < 4; ++j) { v0[j] = x0[j] + sigmoidf_(acc[ai][bj][m][0][j] + b0[j]) * p0[j]; v1[j] = x1[j] + sigmoidf_(acc[ai][bj][m][1][j] + b1[j]) * p1[j]; }
;                     if (out) { *(f32x4*)(out + o) = v0; *(f32x4*)(out + o + 4) = v1; }
;                     if (xbn) { u32x4 w; w.x = cvt_pk_bf16(v0[0], v0[1]); w.y = cvt_pk_bf16(v0[2], v0[3]); w.z = cvt_pk_bf16(v1[0], v1[1]); w.w = cvt_pk_bf16(v1[2], v1[3]); *(u32x4*)(xbn + o) = w; }
	v_lshlrev_b32_e32 v138, 16, v180
	v_and_b32_e32 v139, 0xffff0000, v180
	v_lshlrev_b32_e32 v140, 16, v181
	v_and_b32_e32 v141, 0xffff0000, v181
	v_lshlrev_b32_e32 v144, 16, v182
	v_and_b32_e32 v145, 0xffff0000, v182
	v_lshlrev_b32_e32 v146, 16, v183
	v_and_b32_e32 v147, 0xffff0000, v183
	v_lshlrev_b32_e32 v154, 16, v184
	v_and_b32_e32 v155, 0xffff0000, v184
	v_lshlrev_b32_e32 v156, 16, v185
	v_and_b32_e32 v157, 0xffff0000, v185
	v_lshlrev_b32_e32 v158, 16, v186
	v_and_b32_e32 v159, 0xffff0000, v186
	v_lshlrev_b32_e32 v160, 16, v187
	v_and_b32_e32 v161, 0xffff0000, v187
	v_pk_fma_f32 v[116:117], v[116:117], v[154:155], v[138:139]
	v_pk_fma_f32 v[118:119], v[118:119], v[156:157], v[140:141]
	v_pk_fma_f32 v[112:113], v[112:113], v[158:159], v[144:145]
	v_pk_fma_f32 v[114:115], v[114:115], v[160:161], v[146:147]
	global_store_dwordx4 v169, v[116:119], s[10:11] offset:512
	global_store_dwordx4 v169, v[112:115], s[10:11] offset:528
	v_add_u32_e32 v148, 0x40000, v245
	global_load_dwordx4 v[180:183], v148, s[94:95]
	global_load_dwordx4 v[184:187], v148, s[20:21]
	v_pk_add_f32 v[108:109], v[108:109], v[212:213]
	v_pk_add_f32 v[110:111], v[110:111], v[214:215]
	v_pk_add_f32 v[104:105], v[104:105], v[216:217]
	v_pk_add_f32 v[106:107], v[106:107], v[218:219]
	v_pk_mul_f32 v[108:109], v[108:109], v[246:247]
	v_pk_mul_f32 v[110:111], v[110:111], v[246:247]
	v_pk_mul_f32 v[104:105], v[104:105], v[246:247]
	v_pk_mul_f32 v[106:107], v[106:107], v[246:247]
	v_exp_f32_e32 v104, v104
	v_exp_f32_e32 v105, v105
	v_exp_f32_e32 v106, v106
	v_exp_f32_e32 v107, v107
	v_exp_f32_e32 v108, v108
	v_exp_f32_e32 v109, v109
	v_exp_f32_e32 v110, v110
	v_exp_f32_e32 v111, v111
	v_pk_add_f32 v[108:109], v[108:109], v[236:237]
	v_pk_add_f32 v[110:111], v[110:111], v[236:237]
	v_pk_add_f32 v[104:105], v[104:105], v[236:237]
	v_pk_add_f32 v[106:107], v[106:107], v[236:237]
	v_rcp_f32_e32 v104, v104
	v_rcp_f32_e32 v105, v105
	v_rcp_f32_e32 v106, v106
	v_rcp_f32_e32 v107, v107
	v_rcp_f32_e32 v108, v108
	v_rcp_f32_e32 v109, v109
	v_rcp_f32_e32 v110, v110
	v_rcp_f32_e32 v111, v111
	s_waitcnt vmcnt(16)
	v_lshlrev_b32_e32 v138, 16, v188
	v_and_b32_e32 v139, 0xffff0000, v188
	v_lshlrev_b32_e32 v140, 16, v189
	v_and_b32_e32 v141, 0xffff0000, v189
	v_lshlrev_b32_e32 v144, 16, v190
	v_and_b32_e32 v145, 0xffff0000, v190
	v_lshlrev_b32_e32 v146, 16, v191
	v_and_b32_e32 v147, 0xffff0000, v191
	v_lshlrev_b32_e32 v154, 16, v192
	v_and_b32_e32 v155, 0xffff0000, v192
	v_lshlrev_b32_e32 v156, 16, v193
	v_and_b32_e32 v157, 0xffff0000, v193
	v_lshlrev_b32_e32 v158, 16, v194
	v_and_b32_e32 v159, 0xffff0000, v194
	v_lshlrev_b32_e32 v160, 16, v195
	v_and_b32_e32 v161, 0xffff0000, v195
	v_pk_fma_f32 v[108:109], v[108:109], v[154:155], v[138:139]
	v_pk_fma_f32 v[110:111], v[110:111], v[156:157], v[140:141]
	v_pk_fma_f32 v[104:105], v[104:105], v[158:159], v[144:145]
	v_pk_fma_f32 v[106:107], v[106:107], v[160:161], v[146:147]
	v_add_u32_e32 v239, 0x10000, v238
	global_store_dwordx4 v239, v[108:111], s[10:11]
	global_store_dwordx4 v239, v[104:107], s[10:11] offset:16
	global_load_dwordx4 v[188:191], v148, s[94:95] offset:256
	global_load_dwordx4 v[192:195], v148, s[20:21] offset:256
	v_pk_add_f32 v[100:101], v[100:101], v[220:221]
	v_pk_add_f32 v[102:103], v[102:103], v[222:223]
	v_pk_add_f32 v[96:97], v[96:97], v[224:225]
	v_pk_add_f32 v[98:99], v[98:99], v[226:227]
	v_pk_mul_f32 v[100:101], v[100:101], v[246:247]
	v_pk_mul_f32 v[102:103], v[102:103], v[246:247]
	v_pk_mul_f32 v[96:97], v[96:97], v[246:247]
	v_pk_mul_f32 v[98:99], v[98:99], v[246:247]
	v_exp_f32_e32 v96, v96
	v_exp_f32_e32 v97, v97
	v_exp_f32_e32 v98, v98
	v_exp_f32_e32 v99, v99
	v_exp_f32_e32 v100, v100
	v_exp_f32_e32 v101, v101
	v_exp_f32_e32 v102, v102
	v_exp_f32_e32 v103, v103
	v_pk_add_f32 v[100:101], v[100:101], v[236:237]
	v_pk_add_f32 v[102:103], v[102:103], v[236:237]
	v_pk_add_f32 v[96:97], v[96:97], v[236:237]
	v_pk_add_f32 v[98:99], v[98:99], v[236:237]
	v_rcp_f32_e32 v96, v96
	v_rcp_f32_e32 v97, v97
	v_rcp_f32_e32 v98, v98
	v_rcp_f32_e32 v99, v99
	v_rcp_f32_e32 v100, v100
	v_rcp_f32_e32 v101, v101
	v_rcp_f32_e32 v102, v102
	v_rcp_f32_e32 v103, v103
	s_waitcnt vmcnt(18)
	v_lshlrev_b32_e32 v138, 16, v196
	v_and_b32_e32 v139, 0xffff0000, v196
	v_lshlrev_b32_e32 v140, 16, v197
	v_and_b32_e32 v141, 0xffff0000, v197
	v_lshlrev_b32_e32 v144, 16, v198
	v_and_b32_e32 v145, 0xffff0000, v198
	v_lshlrev_b32_e32 v146, 16, v199
	v_and_b32_e32 v147, 0xffff0000, v199
	v_lshlrev_b32_e32 v154, 16, v200
	v_and_b32_e32 v155, 0xffff0000, v200
	v_lshlrev_b32_e32 v156, 16, v201
	v_and_b32_e32 v157, 0xffff0000, v201
	v_lshlrev_b32_e32 v158, 16, v202
	v_and_b32_e32 v159, 0xffff0000, v202
	v_lshlrev_b32_e32 v160, 16, v203
	v_and_b32_e32 v161, 0xffff0000, v203
	v_pk_fma_f32 v[100:101], v[100:101], v[154:155], v[138:139]
	v_pk_fma_f32 v[102:103], v[102:103], v[156:157], v[140:141]
	v_pk_fma_f32 v[96:97], v[96:97], v[158:159], v[144:145]
	v_pk_fma_f32 v[98:99], v[98:99], v[160:161], v[146:147]
	global_store_dwordx4 v239, v[100:103], s[10:11] offset:512
	global_store_dwordx4 v239, v[96:99], s[10:11] offset:528
	v_add_u32_e32 v149, 0x48000, v245
	global_load_dwordx4 v[196:199], v149, s[94:95]
	global_load_dwordx4 v[200:203], v149, s[20:21]
	v_pk_add_f32 v[92:93], v[92:93], v[212:213]
	v_pk_add_f32 v[94:95], v[94:95], v[214:215]
	v_pk_add_f32 v[88:89], v[88:89], v[216:217]
	v_pk_add_f32 v[90:91], v[90:91], v[218:219]
	v_pk_mul_f32 v[92:93], v[92:93], v[246:247]
	v_pk_mul_f32 v[94:95], v[94:95], v[246:247]
	v_pk_mul_f32 v[88:89], v[88:89], v[246:247]
	v_pk_mul_f32 v[90:91], v[90:91], v[246:247]
	v_exp_f32_e32 v88, v88
	v_exp_f32_e32 v89, v89
	v_exp_f32_e32 v90, v90
	v_exp_f32_e32 v91, v91
	v_exp_f32_e32 v92, v92
	v_exp_f32_e32 v93, v93
	v_exp_f32_e32 v94, v94
	v_exp_f32_e32 v95, v95
	v_pk_add_f32 v[92:93], v[92:93], v[236:237]
	v_pk_add_f32 v[94:95], v[94:95], v[236:237]
	v_pk_add_f32 v[88:89], v[88:89], v[236:237]
	v_pk_add_f32 v[90:91], v[90:91], v[236:237]
	v_rcp_f32_e32 v88, v88
	v_rcp_f32_e32 v89, v89
	v_rcp_f32_e32 v90, v90
	v_rcp_f32_e32 v91, v91
	v_rcp_f32_e32 v92, v92
	v_rcp_f32_e32 v93, v93
	v_rcp_f32_e32 v94, v94
	v_rcp_f32_e32 v95, v95
	s_waitcnt vmcnt(20)
; DI float bflo(unsigned w) { return __uint_as_float(w << 16); }
; DI float bfhi(unsigned w) { return __uint_as_float(w & 0xffff0000u); }
; DI unsigned cvt_pk_bf16(float lo, float hi) { unsigned r; asm volatile("v_cvt_pk_bf16_f32 %0, %1, %2" : "=v"(r) : "v"(lo), "v"(hi)); return r; }
; DI float sigmoidf_(float x) { return __builtin_amdgcn_rcpf(1.0f + __expf(-x)); }
;     DI void operator()(const f32x4 (&acc)[2][2][4][2], const pg8::Unit& u, int wr, int wc, int fr, int fq) const {
;         const int row0 = u.pm * 256 + wr * 64 + fr, col0 = u.pn * 256 + wc * 32 + 8 * fq;
; #pragma unroll
;         for (int ai = 0; ai < 2; ++ai)
; #pragma unroll
;             for (int m = 0; m < 4; ++m) {
;                 const size_t off = (size_t)(row0 + ai * 128 + m * 16) * D_ + col0;
; #pragma unroll
;                 for (int bj = 0; bj < 2; ++bj) {
;                     const size_t o = off + bj * 128;
;                     const f32x4 b0 = *(const f32x4*)(bg + col0 + bj * 128), b1 = *(const f32x4*)(bg + col0 + bj * 128 + 4);
;                     const u32x4 rb = *(const u32x4*)(xb + o);
;                     const u32x4 pb = *(const u32x4*)(pp + o);
;                     const f32x4 x0 = (f32x4){bflo(rb.x), bfhi(rb.x), bflo(rb.y), bfhi(rb.y)}, x1 = (f32x4){bflo(rb.z), bfhi(rb.z), bflo(rb.w), bfhi(rb.w)};
;                     const f32x4 p0 = (f32x4){bflo(pb.x), bfhi(pb.x), bflo(pb.y), bfhi(pb.y)}, p1 = (f32x4){bflo(pb.z), bfhi(pb.z), bflo(pb.w), bfhi(pb.w)};
;                     f32x4 v0, v1;
; #pragma unroll
;                     for (int j = 0; j < 4; ++j) { v0[j] = x0[j] + sigmoidf_(acc[ai][bj][m][0][j] + b0[j]) * p0[j]; v1[j] = x1[j] + sigmoidf_(acc[ai][bj][m][1][j] + b1[j]) * p1[j]; }
;                     if (out) { *(f32x4*)(out + o) = v0; *(f32x4*)(out + o + 4) = v1; }
;                     if (xbn) { u32x4 w; w.x = cvt_pk_bf16(v0[0], v0[1]); w.y = cvt_pk_bf16(v0[2], v0[3]); w.z = cvt_pk_bf16(v1[0], v1[1]); w.w = cvt_pk_bf16(v1[2], v1[3]); *(u32x4*)(xbn + o) = w; }
	v_lshlrev_b32_e32 v138, 16, v204
	v_and_b32_e32 v139, 0xffff0000, v204
	v_lshlrev_b32_e32 v140, 16, v205
	v_and_b32_e32 v141, 0xffff0000, v205
	v_lshlrev_b32_e32 v144, 16, v206
	v_and_b32_e32 v145, 0xffff0000, v206
	v_lshlrev_b32_e32 v146, 16, v207
	v_and_b32_e32 v147, 0xffff0000, v207
	v_lshlrev_b32_e32 v154, 16, v208
	v_and_b32_e32 v155, 0xffff0000, v208
	v_lshlrev_b32_e32 v156, 16, v209
	v_and_b32_e32 v157, 0xffff0000, v209
	v_lshlrev_b32_e32 v158, 16, v210
	v_and_b32_e32 v159, 0xffff0000, v210
	v_lshlrev_b32_e32 v160, 16, v211
	v_and_b32_e32 v161, 0xffff0000, v211
	v_pk_fma_f32 v[92:93], v[92:93], v[154:155], v[138:139]
	v_pk_fma_f32 v[94:95], v[94:95], v[156:157], v[140:141]
	v_pk_fma_f32 v[88:89], v[88:89], v[158:159], v[144:145]
	v_pk_fma_f32 v[90:91], v[90:91], v[160:161], v[146:147]
	v_add_u32_e32 v169, 0x20000, v238
	global_store_dwordx4 v169, v[92:95], s[10:11]
	global_store_dwordx4 v169, v[88:91], s[10:11] offset:16
	global_load_dwordx4 v[204:207], v149, s[94:95] offset:256
	global_load_dwordx4 v[208:211], v149, s[20:21] offset:256
	v_pk_add_f32 v[84:85], v[84:85], v[220:221]
	v_pk_add_f32 v[86:87], v[86:87], v[222:223]
	v_pk_add_f32 v[80:81], v[80:81], v[224:225]
	v_pk_add_f32 v[82:83], v[82:83], v[226:227]
	v_pk_mul_f32 v[84:85], v[84:85], v[246:247]
	v_pk_mul_f32 v[86:87], v[86:87], v[246:247]
	v_pk_mul_f32 v[80:81], v[80:81], v[246:247]
	v_pk_mul_f32 v[82:83], v[82:83], v[246:247]
	v_exp_f32_e32 v80, v80
	v_exp_f32_e32 v81, v81
	v_exp_f32_e32 v82, v82
	v_exp_f32_e32 v83, v83
	v_exp_f32_e32 v84, v84
	v_exp_f32_e32 v85, v85
	v_exp_f32_e32 v86, v86
	v_exp_f32_e32 v87, v87
	v_pk_add_f32 v[84:85], v[84:85], v[236:237]
	v_pk_add_f32 v[86:87], v[86:87], v[236:237]
	v_pk_add_f32 v[80:81], v[80:81], v[236:237]
	v_pk_add_f32 v[82:83], v[82:83], v[236:237]
	v_rcp_f32_e32 v80, v80
	v_rcp_f32_e32 v81, v81
	v_rcp_f32_e32 v82, v82
	v_rcp_f32_e32 v83, v83
	v_rcp_f32_e32 v84, v84
	v_rcp_f32_e32 v85, v85
	v_rcp_f32_e32 v86, v86
	v_rcp_f32_e32 v87, v87
	s_waitcnt vmcnt(22)
	v_lshlrev_b32_e32 v138, 16, v228
	v_and_b32_e32 v139, 0xffff0000, v228
	v_lshlrev_b32_e32 v140, 16, v229
	v_and_b32_e32 v141, 0xffff0000, v229
	v_lshlrev_b32_e32 v144, 16, v230
	v_and_b32_e32 v145, 0xffff0000, v230
	v_lshlrev_b32_e32 v146, 16, v231
	v_and_b32_e32 v147, 0xffff0000, v231
	v_lshlrev_b32_e32 v154, 16, v232
	v_and_b32_e32 v155, 0xffff0000, v232
	v_lshlrev_b32_e32 v156, 16, v233
	v_and_b32_e32 v157, 0xffff0000, v233
	v_lshlrev_b32_e32 v158, 16, v234
	v_and_b32_e32 v159, 0xffff0000, v234
	v_lshlrev_b32_e32 v160, 16, v235
	v_and_b32_e32 v161, 0xffff0000, v235
	v_pk_fma_f32 v[84:85], v[84:85], v[154:155], v[138:139]
	v_pk_fma_f32 v[86:87], v[86:87], v[156:157], v[140:141]
	v_pk_fma_f32 v[80:81], v[80:81], v[158:159], v[144:145]
	v_pk_fma_f32 v[82:83], v[82:83], v[160:161], v[146:147]
	global_store_dwordx4 v169, v[84:87], s[10:11] offset:512
	global_store_dwordx4 v169, v[80:83], s[10:11] offset:528
	v_add_u32_e32 v148, 0x50000, v245
	global_load_dwordx4 v[228:231], v148, s[94:95]
	global_load_dwordx4 v[232:235], v148, s[20:21]
	v_pk_add_f32 v[76:77], v[76:77], v[212:213]
	v_pk_add_f32 v[78:79], v[78:79], v[214:215]
	v_pk_add_f32 v[72:73], v[72:73], v[216:217]
	v_pk_add_f32 v[74:75], v[74:75], v[218:219]
	v_pk_mul_f32 v[76:77], v[76:77], v[246:247]
	v_pk_mul_f32 v[78:79], v[78:79], v[246:247]
	v_pk_mul_f32 v[72:73], v[72:73], v[246:247]
	v_pk_mul_f32 v[74:75], v[74:75], v[246:247]
	v_exp_f32_e32 v72, v72
	v_exp_f32_e32 v73, v73
	v_exp_f32_e32 v74, v74
	v_exp_f32_e32 v75, v75
	v_exp_f32_e32 v76, v76
	v_exp_f32_e32 v77, v77
	v_exp_f32_e32 v78, v78
	v_exp_f32_e32 v79, v79
	v_pk_add_f32 v[76:77], v[76:77], v[236:237]
	v_pk_add_f32 v[78:79], v[78:79], v[236:237]
	v_pk_add_f32 v[72:73], v[72:73], v[236:237]
	v_pk_add_f32 v[74:75], v[74:75], v[236:237]
	v_rcp_f32_e32 v72, v72
	v_rcp_f32_e32 v73, v73
	v_rcp_f32_e32 v74, v74
	v_rcp_f32_e32 v75, v75
	v_rcp_f32_e32 v76, v76
	v_rcp_f32_e32 v77, v77
	v_rcp_f32_e32 v78, v78
	v_rcp_f32_e32 v79, v79
	s_waitcnt vmcnt(24)
	v_lshlrev_b32_e32 v138, 16, v128
	v_and_b32_e32 v139, 0xffff0000, v128
	v_lshlrev_b32_e32 v140, 16, v129
	v_and_b32_e32 v141, 0xffff0000, v129
	v_lshlrev_b32_e32 v144, 16, v130
	v_and_b32_e32 v145, 0xffff0000, v130
	v_lshlrev_b32_e32 v146, 16, v131
	v_and_b32_e32 v147, 0xffff0000, v131
	v_lshlrev_b32_e32 v154, 16, v132
	v_and_b32_e32 v155, 0xffff0000, v132
	v_lshlrev_b32_e32 v156, 16, v133
	v_and_b32_e32 v157, 0xffff0000, v133
	v_lshlrev_b32_e32 v158, 16, v134
	v_and_b32_e32 v159, 0xffff0000, v134
	v_lshlrev_b32_e32 v160, 16, v135
	v_and_b32_e32 v161, 0xffff0000, v135
	v_pk_fma_f32 v[76:77], v[76:77], v[154:155], v[138:139]
	v_pk_fma_f32 v[78:79], v[78:79], v[156:157], v[140:141]
	v_pk_fma_f32 v[72:73], v[72:73], v[158:159], v[144:145]
	v_pk_fma_f32 v[74:75], v[74:75], v[160:161], v[146:147]
	v_add_u32_e32 v239, 0x30000, v238
	global_store_dwordx4 v239, v[76:79], s[10:11]
	global_store_dwordx4 v239, v[72:75], s[10:11] offset:16
	global_load_dwordx4 v[128:131], v148, s[94:95] offset:256
	global_load_dwordx4 v[132:135], v148, s[20:21] offset:256
	v_pk_add_f32 v[68:69], v[68:69], v[220:221]
	v_pk_add_f32 v[70:71], v[70:71], v[222:223]
	v_pk_add_f32 v[64:65], v[64:65], v[224:225]
	v_pk_add_f32 v[66:67], v[66:67], v[226:227]
	v_pk_mul_f32 v[68:69], v[68:69], v[246:247]
	v_pk_mul_f32 v[70:71], v[70:71], v[246:247]
	v_pk_mul_f32 v[64:65], v[64:65], v[246:247]
	v_pk_mul_f32 v[66:67], v[66:67], v[246:247]
	v_exp_f32_e32 v64, v64
	v_exp_f32_e32 v65, v65
	v_exp_f32_e32 v66, v66
	v_exp_f32_e32 v67, v67
	v_exp_f32_e32 v68, v68
	v_exp_f32_e32 v69, v69
	v_exp_f32_e32 v70, v70
	v_exp_f32_e32 v71, v71
	v_pk_add_f32 v[68:69], v[68:69], v[236:237]
	v_pk_add_f32 v[70:71], v[70:71], v[236:237]
	v_pk_add_f32 v[64:65], v[64:65], v[236:237]
	v_pk_add_f32 v[66:67], v[66:67], v[236:237]
	v_rcp_f32_e32 v64, v64
	v_rcp_f32_e32 v65, v65
	v_rcp_f32_e32 v66, v66
	v_rcp_f32_e32 v67, v67
	v_rcp_f32_e32 v68, v68
	v_rcp_f32_e32 v69, v69
	v_rcp_f32_e32 v70, v70
	v_rcp_f32_e32 v71, v71
	s_waitcnt vmcnt(24)
; DI float bflo(unsigned w) { return __uint_as_float(w << 16); }
; DI float bfhi(unsigned w) { return __uint_as_float(w & 0xffff0000u); }
; DI unsigned cvt_pk_bf16(float lo, float hi) { unsigned r; asm volatile("v_cvt_pk_bf16_f32 %0, %1, %2" : "=v"(r) : "v"(lo), "v"(hi)); return r; }
; DI float sigmoidf_(float x) { return __builtin_amdgcn_rcpf(1.0f + __expf(-x)); }
;     DI void operator()(const f32x4 (&acc)[2][2][4][2], const pg8::Unit& u, int wr, int wc, int fr, int fq) const {
;         const int row0 = u.pm * 256 + wr * 64 + fr, col0 = u.pn * 256 + wc * 32 + 8 * fq;
; #pragma unroll
;         for (int ai = 0; ai < 2; ++ai)
; #pragma unroll
;             for (int m = 0; m < 4; ++m) {
;                 const size_t off = (size_t)(row0 + ai * 128 + m * 16) * D_ + col0;
; #pragma unroll
;                 for (int bj = 0; bj < 2; ++bj) {
;                     const size_t o = off + bj * 128;
;                     const f32x4 b0 = *(const f32x4*)(bg + col0 + bj * 128), b1 = *(const f32x4*)(bg + col0 + bj * 128 + 4);
;                     const u32x4 rb = *(const u32x4*)(xb + o);
;                     const u32x4 pb = *(const u32x4*)(pp + o);
;                     const f32x4 x0 = (f32x4){bflo(rb.x), bfhi(rb.x), bflo(rb.y), bfhi(rb.y)}, x1 = (f32x4){bflo(rb.z), bfhi(rb.z), bflo(rb.w), bfhi(rb.w)};
;                     const f32x4 p0 = (f32x4){bflo(pb.x), bfhi(pb.x), bflo(pb.y), bfhi(pb.y)}, p1 = (f32x4){bflo(pb.z), bfhi(pb.z), bflo(pb.w), bfhi(pb.w)};
;                     f32x4 v0, v1;
; #pragma unroll
;                     for (int j = 0; j < 4; ++j) { v0[j] = x0[j] + sigmoidf_(acc[ai][bj][m][0][j] + b0[j]) * p0[j]; v1[j] = x1[j] + sigmoidf_(acc[ai][bj][m][1][j] + b1[j]) * p1[j]; }
;                     if (out) { *(f32x4*)(out + o) = v0; *(f32x4*)(out + o + 4) = v1; }
;                     if (xbn) { u32x4 w; w.x = cvt_pk_bf16(v0[0], v0[1]); w.y = cvt_pk_bf16(v0[2], v0[3]); w.z = cvt_pk_bf16(v1[0], v1[1]); w.w = cvt_pk_bf16(v1[2], v1[3]); *(u32x4*)(xbn + o) = w; }
	v_lshlrev_b32_e32 v138, 16, v172
	v_and_b32_e32 v139, 0xffff0000, v172
	v_lshlrev_b32_e32 v140, 16, v173
	v_and_b32_e32 v141, 0xffff0000, v173
	v_lshlrev_b32_e32 v144, 16, v174
	v_and_b32_e32 v145, 0xffff0000, v174
	v_lshlrev_b32_e32 v146, 16, v175
	v_and_b32_e32 v147, 0xffff0000, v175
	v_lshlrev_b32_e32 v154, 16, v176
	v_and_b32_e32 v155, 0xffff0000, v176
	v_lshlrev_b32_e32 v156, 16, v177
	v_and_b32_e32 v157, 0xffff0000, v177
	v_lshlrev_b32_e32 v158, 16, v178
	v_and_b32_e32 v159, 0xffff0000, v178
	v_lshlrev_b32_e32 v160, 16, v179
	v_and_b32_e32 v161, 0xffff0000, v179
	v_pk_fma_f32 v[68:69], v[68:69], v[154:155], v[138:139]
	v_pk_fma_f32 v[70:71], v[70:71], v[156:157], v[140:141]
	v_pk_fma_f32 v[64:65], v[64:65], v[158:159], v[144:145]
	v_pk_fma_f32 v[66:67], v[66:67], v[160:161], v[146:147]
	global_store_dwordx4 v239, v[68:71], s[10:11] offset:512
	global_store_dwordx4 v239, v[64:67], s[10:11] offset:528
	v_add_u32_e32 v149, 0x58000, v245
	global_load_dwordx4 v[172:175], v149, s[94:95]
	global_load_dwordx4 v[176:179], v149, s[20:21]
	v_pk_add_f32 v[60:61], v[60:61], v[212:213]
	v_pk_add_f32 v[62:63], v[62:63], v[214:215]
	v_pk_add_f32 v[56:57], v[56:57], v[216:217]
	v_pk_add_f32 v[58:59], v[58:59], v[218:219]
	v_pk_mul_f32 v[60:61], v[60:61], v[246:247]
	v_pk_mul_f32 v[62:63], v[62:63], v[246:247]
	v_pk_mul_f32 v[56:57], v[56:57], v[246:247]
	v_pk_mul_f32 v[58:59], v[58:59], v[246:247]
	v_exp_f32_e32 v56, v56
	v_exp_f32_e32 v57, v57
	v_exp_f32_e32 v58, v58
	v_exp_f32_e32 v59, v59
	v_exp_f32_e32 v60, v60
	v_exp_f32_e32 v61, v61
	v_exp_f32_e32 v62, v62
	v_exp_f32_e32 v63, v63
	v_pk_add_f32 v[60:61], v[60:61], v[236:237]
	v_pk_add_f32 v[62:63], v[62:63], v[236:237]
	v_pk_add_f32 v[56:57], v[56:57], v[236:237]
	v_pk_add_f32 v[58:59], v[58:59], v[236:237]
	v_rcp_f32_e32 v56, v56
	v_rcp_f32_e32 v57, v57
	v_rcp_f32_e32 v58, v58
	v_rcp_f32_e32 v59, v59
	v_rcp_f32_e32 v60, v60
	v_rcp_f32_e32 v61, v61
	v_rcp_f32_e32 v62, v62
	v_rcp_f32_e32 v63, v63
	s_waitcnt vmcnt(24)
	v_lshlrev_b32_e32 v138, 16, v180
	v_and_b32_e32 v139, 0xffff0000, v180
	v_lshlrev_b32_e32 v140, 16, v181
	v_and_b32_e32 v141, 0xffff0000, v181
	v_lshlrev_b32_e32 v144, 16, v182
	v_and_b32_e32 v145, 0xffff0000, v182
	v_lshlrev_b32_e32 v146, 16, v183
	v_and_b32_e32 v147, 0xffff0000, v183
	v_lshlrev_b32_e32 v154, 16, v184
	v_and_b32_e32 v155, 0xffff0000, v184
	v_lshlrev_b32_e32 v156, 16, v185
	v_and_b32_e32 v157, 0xffff0000, v185
	v_lshlrev_b32_e32 v158, 16, v186
	v_and_b32_e32 v159, 0xffff0000, v186
	v_lshlrev_b32_e32 v160, 16, v187
	v_and_b32_e32 v161, 0xffff0000, v187
	v_pk_fma_f32 v[60:61], v[60:61], v[154:155], v[138:139]
	v_pk_fma_f32 v[62:63], v[62:63], v[156:157], v[140:141]
	v_pk_fma_f32 v[56:57], v[56:57], v[158:159], v[144:145]
	v_pk_fma_f32 v[58:59], v[58:59], v[160:161], v[146:147]
	v_add_u32_e32 v169, 0x80000, v238
	global_store_dwordx4 v169, v[60:63], s[10:11]
	global_store_dwordx4 v169, v[56:59], s[10:11] offset:16
	global_load_dwordx4 v[180:183], v149, s[94:95] offset:256
	global_load_dwordx4 v[184:187], v149, s[20:21] offset:256
	v_pk_add_f32 v[52:53], v[52:53], v[220:221]
	v_pk_add_f32 v[54:55], v[54:55], v[222:223]
	v_pk_add_f32 v[48:49], v[48:49], v[224:225]
	v_pk_add_f32 v[50:51], v[50:51], v[226:227]
	v_pk_mul_f32 v[52:53], v[52:53], v[246:247]
	v_pk_mul_f32 v[54:55], v[54:55], v[246:247]
	v_pk_mul_f32 v[48:49], v[48:49], v[246:247]
	v_pk_mul_f32 v[50:51], v[50:51], v[246:247]
	v_exp_f32_e32 v48, v48
	v_exp_f32_e32 v49, v49
	v_exp_f32_e32 v50, v50
	v_exp_f32_e32 v51, v51
	v_exp_f32_e32 v52, v52
	v_exp_f32_e32 v53, v53
	v_exp_f32_e32 v54, v54
	v_exp_f32_e32 v55, v55
	v_pk_add_f32 v[52:53], v[52:53], v[236:237]
	v_pk_add_f32 v[54:55], v[54:55], v[236:237]
	v_pk_add_f32 v[48:49], v[48:49], v[236:237]
	v_pk_add_f32 v[50:51], v[50:51], v[236:237]
	v_rcp_f32_e32 v48, v48
	v_rcp_f32_e32 v49, v49
	v_rcp_f32_e32 v50, v50
	v_rcp_f32_e32 v51, v51
	v_rcp_f32_e32 v52, v52
	v_rcp_f32_e32 v53, v53
	v_rcp_f32_e32 v54, v54
	v_rcp_f32_e32 v55, v55
	s_waitcnt vmcnt(24)
	v_lshlrev_b32_e32 v138, 16, v188
	v_and_b32_e32 v139, 0xffff0000, v188
	v_lshlrev_b32_e32 v140, 16, v189
	v_and_b32_e32 v141, 0xffff0000, v189
	v_lshlrev_b32_e32 v144, 16, v190
	v_and_b32_e32 v145, 0xffff0000, v190
	v_lshlrev_b32_e32 v146, 16, v191
	v_and_b32_e32 v147, 0xffff0000, v191
	v_lshlrev_b32_e32 v154, 16, v192
	v_and_b32_e32 v155, 0xffff0000, v192
	v_lshlrev_b32_e32 v156, 16, v193
	v_and_b32_e32 v157, 0xffff0000, v193
	v_lshlrev_b32_e32 v158, 16, v194
	v_and_b32_e32 v159, 0xffff0000, v194
	v_lshlrev_b32_e32 v160, 16, v195
	v_and_b32_e32 v161, 0xffff0000, v195
	v_pk_fma_f32 v[52:53], v[52:53], v[154:155], v[138:139]
	v_pk_fma_f32 v[54:55], v[54:55], v[156:157], v[140:141]
	v_pk_fma_f32 v[48:49], v[48:49], v[158:159], v[144:145]
	v_pk_fma_f32 v[50:51], v[50:51], v[160:161], v[146:147]
	global_store_dwordx4 v169, v[52:55], s[10:11] offset:512
	global_store_dwordx4 v169, v[48:51], s[10:11] offset:528
	v_pk_add_f32 v[44:45], v[44:45], v[212:213]
	v_pk_add_f32 v[46:47], v[46:47], v[214:215]
	v_pk_add_f32 v[40:41], v[40:41], v[216:217]
	v_pk_add_f32 v[42:43], v[42:43], v[218:219]
	v_pk_mul_f32 v[44:45], v[44:45], v[246:247]
	v_pk_mul_f32 v[46:47], v[46:47], v[246:247]
	v_pk_mul_f32 v[40:41], v[40:41], v[246:247]
	v_pk_mul_f32 v[42:43], v[42:43], v[246:247]
	v_exp_f32_e32 v40, v40
	v_exp_f32_e32 v41, v41
	v_exp_f32_e32 v42, v42
	v_exp_f32_e32 v43, v43
	v_exp_f32_e32 v44, v44
	v_exp_f32_e32 v45, v45
	v_exp_f32_e32 v46, v46
	v_exp_f32_e32 v47, v47
	v_pk_add_f32 v[44:45], v[44:45], v[236:237]
	v_pk_add_f32 v[46:47], v[46:47], v[236:237]
	v_pk_add_f32 v[40:41], v[40:41], v[236:237]
	v_pk_add_f32 v[42:43], v[42:43], v[236:237]
	v_rcp_f32_e32 v40, v40
	v_rcp_f32_e32 v41, v41
	v_rcp_f32_e32 v42, v42
	v_rcp_f32_e32 v43, v43
	v_rcp_f32_e32 v44, v44
	v_rcp_f32_e32 v45, v45
	v_rcp_f32_e32 v46, v46
	v_rcp_f32_e32 v47, v47
	s_waitcnt vmcnt(22)
; DI float bflo(unsigned w) { return __uint_as_float(w << 16); }
; DI float bfhi(unsigned w) { return __uint_as_float(w & 0xffff0000u); }
; DI unsigned cvt_pk_bf16(float lo, float hi) { unsigned r; asm volatile("v_cvt_pk_bf16_f32 %0, %1, %2" : "=v"(r) : "v"(lo), "v"(hi)); return r; }
; DI float sigmoidf_(float x) { return __builtin_amdgcn_rcpf(1.0f + __expf(-x)); }
;     DI void operator()(const f32x4 (&acc)[2][2][4][2], const pg8::Unit& u, int wr, int wc, int fr, int fq) const {
;         const int row0 = u.pm * 256 + wr * 64 + fr, col0 = u.pn * 256 + wc * 32 + 8 * fq;
; #pragma unroll
;         for (int ai = 0; ai < 2; ++ai)
; #pragma unroll
;             for (int m = 0; m < 4; ++m) {
;                 const size_t off = (size_t)(row0 + ai * 128 + m * 16) * D_ + col0;
; #pragma unroll
;                 for (int bj = 0; bj < 2; ++bj) {
;                     const size_t o = off + bj * 128;
;                     const f32x4 b0 = *(const f32x4*)(bg + col0 + bj * 128), b1 = *(const f32x4*)(bg + col0 + bj * 128 + 4);
;                     const u32x4 rb = *(const u32x4*)(xb + o);
;                     const u32x4 pb = *(const u32x4*)(pp + o);
;                     const f32x4 x0 = (f32x4){bflo(rb.x), bfhi(rb.x), bflo(rb.y), bfhi(rb.y)}, x1 = (f32x4){bflo(rb.z), bfhi(rb.z), bflo(rb.w), bfhi(rb.w)};
;                     const f32x4 p0 = (f32x4){bflo(pb.x), bfhi(pb.x), bflo(pb.y), bfhi(pb.y)}, p1 = (f32x4){bflo(pb.z), bfhi(pb.z), bflo(pb.w), bfhi(pb.w)};
;                     f32x4 v0, v1;
; #pragma unroll
;                     for (int j = 0; j < 4; ++j) { v0[j] = x0[j] + sigmoidf_(acc[ai][bj][m][0][j] + b0[j]) * p0[j]; v1[j] = x1[j] + sigmoidf_(acc[ai][bj][m][1][j] + b1[j]) * p1[j]; }
;                     if (out) { *(f32x4*)(out + o) = v0; *(f32x4*)(out + o + 4) = v1; }
;                     if (xbn) { u32x4 w; w.x = cvt_pk_bf16(v0[0], v0[1]); w.y = cvt_pk_bf16(v0[2], v0[3]); w.z = cvt_pk_bf16(v1[0], v1[1]); w.w = cvt_pk_bf16(v1[2], v1[3]); *(u32x4*)(xbn + o) = w; }
	v_lshlrev_b32_e32 v138, 16, v196
	v_and_b32_e32 v139, 0xffff0000, v196
	v_lshlrev_b32_e32 v140, 16, v197
	v_and_b32_e32 v141, 0xffff0000, v197
	v_lshlrev_b32_e32 v144, 16, v198
	v_and_b32_e32 v145, 0xffff0000, v198
	v_lshlrev_b32_e32 v146, 16, v199
	v_and_b32_e32 v147, 0xffff0000, v199
	v_lshlrev_b32_e32 v154, 16, v200
	v_and_b32_e32 v155, 0xffff0000, v200
	v_lshlrev_b32_e32 v156, 16, v201
	v_and_b32_e32 v157, 0xffff0000, v201
	v_lshlrev_b32_e32 v158, 16, v202
	v_and_b32_e32 v159, 0xffff0000, v202
	v_lshlrev_b32_e32 v160, 16, v203
	v_and_b32_e32 v161, 0xffff0000, v203
	v_pk_fma_f32 v[44:45], v[44:45], v[154:155], v[138:139]
	v_pk_fma_f32 v[46:47], v[46:47], v[156:157], v[140:141]
	v_pk_fma_f32 v[40:41], v[40:41], v[158:159], v[144:145]
	v_pk_fma_f32 v[42:43], v[42:43], v[160:161], v[146:147]
	v_add_u32_e32 v239, 0x90000, v238
	global_store_dwordx4 v239, v[44:47], s[10:11]
	global_store_dwordx4 v239, v[40:43], s[10:11] offset:16
	v_pk_add_f32 v[36:37], v[36:37], v[220:221]
	v_pk_add_f32 v[38:39], v[38:39], v[222:223]
	v_pk_add_f32 v[32:33], v[32:33], v[224:225]
	v_pk_add_f32 v[34:35], v[34:35], v[226:227]
	v_pk_mul_f32 v[36:37], v[36:37], v[246:247]
	v_pk_mul_f32 v[38:39], v[38:39], v[246:247]
	v_pk_mul_f32 v[32:33], v[32:33], v[246:247]
	v_pk_mul_f32 v[34:35], v[34:35], v[246:247]
	v_exp_f32_e32 v32, v32
	v_exp_f32_e32 v33, v33
	v_exp_f32_e32 v34, v34
	v_exp_f32_e32 v35, v35
	v_exp_f32_e32 v36, v36
	v_exp_f32_e32 v37, v37
	v_exp_f32_e32 v38, v38
	v_exp_f32_e32 v39, v39
	v_pk_add_f32 v[36:37], v[36:37], v[236:237]
	v_pk_add_f32 v[38:39], v[38:39], v[236:237]
	v_pk_add_f32 v[32:33], v[32:33], v[236:237]
	v_pk_add_f32 v[34:35], v[34:35], v[236:237]
	v_rcp_f32_e32 v32, v32
	v_rcp_f32_e32 v33, v33
	v_rcp_f32_e32 v34, v34
	v_rcp_f32_e32 v35, v35
	v_rcp_f32_e32 v36, v36
	v_rcp_f32_e32 v37, v37
	v_rcp_f32_e32 v38, v38
	v_rcp_f32_e32 v39, v39
	s_waitcnt vmcnt(20)
	v_lshlrev_b32_e32 v138, 16, v204
	v_and_b32_e32 v139, 0xffff0000, v204
	v_lshlrev_b32_e32 v140, 16, v205
	v_and_b32_e32 v141, 0xffff0000, v205
	v_lshlrev_b32_e32 v144, 16, v206
	v_and_b32_e32 v145, 0xffff0000, v206
	v_lshlrev_b32_e32 v146, 16, v207
	v_and_b32_e32 v147, 0xffff0000, v207
	v_lshlrev_b32_e32 v154, 16, v208
	v_and_b32_e32 v155, 0xffff0000, v208
	v_lshlrev_b32_e32 v156, 16, v209
	v_and_b32_e32 v157, 0xffff0000, v209
	v_lshlrev_b32_e32 v158, 16, v210
	v_and_b32_e32 v159, 0xffff0000, v210
	v_lshlrev_b32_e32 v160, 16, v211
	v_and_b32_e32 v161, 0xffff0000, v211
	v_pk_fma_f32 v[36:37], v[36:37], v[154:155], v[138:139]
	v_pk_fma_f32 v[38:39], v[38:39], v[156:157], v[140:141]
	v_pk_fma_f32 v[32:33], v[32:33], v[158:159], v[144:145]
	v_pk_fma_f32 v[34:35], v[34:35], v[160:161], v[146:147]
	global_store_dwordx4 v239, v[36:39], s[10:11] offset:512
	global_store_dwordx4 v239, v[32:35], s[10:11] offset:528
	v_pk_add_f32 v[28:29], v[28:29], v[212:213]
	v_pk_add_f32 v[30:31], v[30:31], v[214:215]
	v_pk_add_f32 v[24:25], v[24:25], v[216:217]
	v_pk_add_f32 v[26:27], v[26:27], v[218:219]
	v_pk_mul_f32 v[28:29], v[28:29], v[246:247]
	v_pk_mul_f32 v[30:31], v[30:31], v[246:247]
	v_pk_mul_f32 v[24:25], v[24:25], v[246:247]
	v_pk_mul_f32 v[26:27], v[26:27], v[246:247]
	v_exp_f32_e32 v24, v24
	v_exp_f32_e32 v25, v25
	v_exp_f32_e32 v26, v26
	v_exp_f32_e32 v27, v27
	v_exp_f32_e32 v28, v28
	v_exp_f32_e32 v29, v29
	v_exp_f32_e32 v30, v30
	v_exp_f32_e32 v31, v31
	v_pk_add_f32 v[28:29], v[28:29], v[236:237]
	v_pk_add_f32 v[30:31], v[30:31], v[236:237]
	v_pk_add_f32 v[24:25], v[24:25], v[236:237]
	v_pk_add_f32 v[26:27], v[26:27], v[236:237]
	v_rcp_f32_e32 v24, v24
	v_rcp_f32_e32 v25, v25
	v_rcp_f32_e32 v26, v26
	v_rcp_f32_e32 v27, v27
	v_rcp_f32_e32 v28, v28
	v_rcp_f32_e32 v29, v29
	v_rcp_f32_e32 v30, v30
	v_rcp_f32_e32 v31, v31
	s_waitcnt vmcnt(18)
	v_lshlrev_b32_e32 v138, 16, v228
	v_and_b32_e32 v139, 0xffff0000, v228
	v_lshlrev_b32_e32 v140, 16, v229
	v_and_b32_e32 v141, 0xffff0000, v229
	v_lshlrev_b32_e32 v144, 16, v230
	v_and_b32_e32 v145, 0xffff0000, v230
	v_lshlrev_b32_e32 v146, 16, v231
	v_and_b32_e32 v147, 0xffff0000, v231
	v_lshlrev_b32_e32 v154, 16, v232
	v_and_b32_e32 v155, 0xffff0000, v232
	v_lshlrev_b32_e32 v156, 16, v233
	v_and_b32_e32 v157, 0xffff0000, v233
	v_lshlrev_b32_e32 v158, 16, v234
	v_and_b32_e32 v159, 0xffff0000, v234
	v_lshlrev_b32_e32 v160, 16, v235
	v_and_b32_e32 v161, 0xffff0000, v235
	v_pk_fma_f32 v[28:29], v[28:29], v[154:155], v[138:139]
	v_pk_fma_f32 v[30:31], v[30:31], v[156:157], v[140:141]
	v_pk_fma_f32 v[24:25], v[24:25], v[158:159], v[144:145]
	v_pk_fma_f32 v[26:27], v[26:27], v[160:161], v[146:147]
	v_add_u32_e32 v169, 0xa0000, v238
	global_store_dwordx4 v169, v[28:31], s[10:11]
	global_store_dwordx4 v169, v[24:27], s[10:11] offset:16
	v_pk_add_f32 v[20:21], v[20:21], v[220:221]
	v_pk_add_f32 v[22:23], v[22:23], v[222:223]
	v_pk_add_f32 v[16:17], v[16:17], v[224:225]
	v_pk_add_f32 v[18:19], v[18:19], v[226:227]
	v_pk_mul_f32 v[20:21], v[20:21], v[246:247]
	v_pk_mul_f32 v[22:23], v[22:23], v[246:247]
	v_pk_mul_f32 v[16:17], v[16:17], v[246:247]
	v_pk_mul_f32 v[18:19], v[18:19], v[246:247]
	v_exp_f32_e32 v16, v16
	v_exp_f32_e32 v17, v17
	v_exp_f32_e32 v18, v18
	v_exp_f32_e32 v19, v19
	v_exp_f32_e32 v20, v20
	v_exp_f32_e32 v21, v21
	v_exp_f32_e32 v22, v22
	v_exp_f32_e32 v23, v23
	v_pk_add_f32 v[20:21], v[20:21], v[236:237]
	v_pk_add_f32 v[22:23], v[22:23], v[236:237]
	v_pk_add_f32 v[16:17], v[16:17], v[236:237]
	v_pk_add_f32 v[18:19], v[18:19], v[236:237]
	v_rcp_f32_e32 v16, v16
	v_rcp_f32_e32 v17, v17
	v_rcp_f32_e32 v18, v18
	v_rcp_f32_e32 v19, v19
	v_rcp_f32_e32 v20, v20
	v_rcp_f32_e32 v21, v21
	v_rcp_f32_e32 v22, v22
	v_rcp_f32_e32 v23, v23
	s_waitcnt vmcnt(16)
; DI float bflo(unsigned w) { return __uint_as_float(w << 16); }
; DI float bfhi(unsigned w) { return __uint_as_float(w & 0xffff0000u); }
; DI unsigned cvt_pk_bf16(float lo, float hi) { unsigned r; asm volatile("v_cvt_pk_bf16_f32 %0, %1, %2" : "=v"(r) : "v"(lo), "v"(hi)); return r; }
; DI float sigmoidf_(float x) { return __builtin_amdgcn_rcpf(1.0f + __expf(-x)); }
;     DI void operator()(const f32x4 (&acc)[2][2][4][2], const pg8::Unit& u, int wr, int wc, int fr, int fq) const {
;         const int row0 = u.pm * 256 + wr * 64 + fr, col0 = u.pn * 256 + wc * 32 + 8 * fq;
; #pragma unroll
;         for (int ai = 0; ai < 2; ++ai)
; #pragma unroll
;             for (int m = 0; m < 4; ++m) {
;                 const size_t off = (size_t)(row0 + ai * 128 + m * 16) * D_ + col0;
; #pragma unroll
;                 for (int bj = 0; bj < 2; ++bj) {
;                     const size_t o = off + bj * 128;
;                     const f32x4 b0 = *(const f32x4*)(bg + col0 + bj * 128), b1 = *(const f32x4*)(bg + col0 + bj * 128 + 4);
;                     const u32x4 rb = *(const u32x4*)(xb + o);
;                     const u32x4 pb = *(const u32x4*)(pp + o);
;                     const f32x4 x0 = (f32x4){bflo(rb.x), bfhi(rb.x), bflo(rb.y), bfhi(rb.y)}, x1 = (f32x4){bflo(rb.z), bfhi(rb.z), bflo(rb.w), bfhi(rb.w)};
;                     const f32x4 p0 = (f32x4){bflo(pb.x), bfhi(pb.x), bflo(pb.y), bfhi(pb.y)}, p1 = (f32x4){bflo(pb.z), bfhi(pb.z), bflo(pb.w), bfhi(pb.w)};
;                     f32x4 v0, v1;
; #pragma unroll
;                     for (int j = 0; j < 4; ++j) { v0[j] = x0[j] + sigmoidf_(acc[ai][bj][m][0][j] + b0[j]) * p0[j]; v1[j] = x1[j] + sigmoidf_(acc[ai][bj][m][1][j] + b1[j]) * p1[j]; }
;                     if (out) { *(f32x4*)(out + o) = v0; *(f32x4*)(out + o + 4) = v1; }
;                     if (xbn) { u32x4 w; w.x = cvt_pk_bf16(v0[0], v0[1]); w.y = cvt_pk_bf16(v0[2], v0[3]); w.z = cvt_pk_bf16(v1[0], v1[1]); w.w = cvt_pk_bf16(v1[2], v1[3]); *(u32x4*)(xbn + o) = w; }
	v_lshlrev_b32_e32 v138, 16, v128
	v_and_b32_e32 v139, 0xffff0000, v128
	v_lshlrev_b32_e32 v140, 16, v129
	v_and_b32_e32 v141, 0xffff0000, v129
	v_lshlrev_b32_e32 v144, 16, v130
	v_and_b32_e32 v145, 0xffff0000, v130
	v_lshlrev_b32_e32 v146, 16, v131
	v_and_b32_e32 v147, 0xffff0000, v131
	v_lshlrev_b32_e32 v154, 16, v132
	v_and_b32_e32 v155, 0xffff0000, v132
	v_lshlrev_b32_e32 v156, 16, v133
	v_and_b32_e32 v157, 0xffff0000, v133
	v_lshlrev_b32_e32 v158, 16, v134
	v_and_b32_e32 v159, 0xffff0000, v134
	v_lshlrev_b32_e32 v160, 16, v135
	v_and_b32_e32 v161, 0xffff0000, v135
	v_pk_fma_f32 v[20:21], v[20:21], v[154:155], v[138:139]
	v_pk_fma_f32 v[22:23], v[22:23], v[156:157], v[140:141]
	v_pk_fma_f32 v[16:17], v[16:17], v[158:159], v[144:145]
	v_pk_fma_f32 v[18:19], v[18:19], v[160:161], v[146:147]
	global_store_dwordx4 v169, v[20:23], s[10:11] offset:512
	global_store_dwordx4 v169, v[16:19], s[10:11] offset:528
	v_pk_add_f32 v[12:13], v[12:13], v[212:213]
	v_pk_add_f32 v[14:15], v[14:15], v[214:215]
	v_pk_add_f32 v[8:9], v[8:9], v[216:217]
	v_pk_add_f32 v[10:11], v[10:11], v[218:219]
	v_pk_mul_f32 v[12:13], v[12:13], v[246:247]
	v_pk_mul_f32 v[14:15], v[14:15], v[246:247]
	v_pk_mul_f32 v[8:9], v[8:9], v[246:247]
	v_pk_mul_f32 v[10:11], v[10:11], v[246:247]
	v_exp_f32_e32 v8, v8
	v_exp_f32_e32 v9, v9
	v_exp_f32_e32 v10, v10
	v_exp_f32_e32 v11, v11
	v_exp_f32_e32 v12, v12
	v_exp_f32_e32 v13, v13
	v_exp_f32_e32 v14, v14
	v_exp_f32_e32 v15, v15
	v_pk_add_f32 v[12:13], v[12:13], v[236:237]
	v_pk_add_f32 v[14:15], v[14:15], v[236:237]
	v_pk_add_f32 v[8:9], v[8:9], v[236:237]
	v_pk_add_f32 v[10:11], v[10:11], v[236:237]
	v_rcp_f32_e32 v8, v8
	v_rcp_f32_e32 v9, v9
	v_rcp_f32_e32 v10, v10
	v_rcp_f32_e32 v11, v11
	v_rcp_f32_e32 v12, v12
	v_rcp_f32_e32 v13, v13
	v_rcp_f32_e32 v14, v14
	v_rcp_f32_e32 v15, v15
	s_waitcnt vmcnt(14)
	v_lshlrev_b32_e32 v138, 16, v172
	v_and_b32_e32 v139, 0xffff0000, v172
	v_lshlrev_b32_e32 v140, 16, v173
	v_and_b32_e32 v141, 0xffff0000, v173
	v_lshlrev_b32_e32 v144, 16, v174
	v_and_b32_e32 v145, 0xffff0000, v174
	v_lshlrev_b32_e32 v146, 16, v175
	v_and_b32_e32 v147, 0xffff0000, v175
	v_lshlrev_b32_e32 v154, 16, v176
	v_and_b32_e32 v155, 0xffff0000, v176
	v_lshlrev_b32_e32 v156, 16, v177
	v_and_b32_e32 v157, 0xffff0000, v177
	v_lshlrev_b32_e32 v158, 16, v178
	v_and_b32_e32 v159, 0xffff0000, v178
	v_lshlrev_b32_e32 v160, 16, v179
	v_and_b32_e32 v161, 0xffff0000, v179
	v_pk_fma_f32 v[12:13], v[12:13], v[154:155], v[138:139]
	v_pk_fma_f32 v[14:15], v[14:15], v[156:157], v[140:141]
	v_pk_fma_f32 v[8:9], v[8:9], v[158:159], v[144:145]
	v_pk_fma_f32 v[10:11], v[10:11], v[160:161], v[146:147]
	v_add_u32_e32 v239, 0xb0000, v238
	global_store_dwordx4 v239, v[12:15], s[10:11]
	global_store_dwordx4 v239, v[8:11], s[10:11] offset:16
	v_pk_add_f32 v[4:5], v[4:5], v[220:221]
	v_pk_add_f32 v[6:7], v[6:7], v[222:223]
	v_pk_add_f32 v[0:1], v[0:1], v[224:225]
	v_pk_add_f32 v[2:3], v[2:3], v[226:227]
	v_pk_mul_f32 v[4:5], v[4:5], v[246:247]
	v_pk_mul_f32 v[6:7], v[6:7], v[246:247]
	v_pk_mul_f32 v[0:1], v[0:1], v[246:247]
	v_pk_mul_f32 v[2:3], v[2:3], v[246:247]
	v_exp_f32_e32 v0, v0
	v_exp_f32_e32 v1, v1
	v_exp_f32_e32 v2, v2
	v_exp_f32_e32 v3, v3
	v_exp_f32_e32 v4, v4
	v_exp_f32_e32 v5, v5
	v_exp_f32_e32 v6, v6
	v_exp_f32_e32 v7, v7
	v_pk_add_f32 v[4:5], v[4:5], v[236:237]
	v_pk_add_f32 v[6:7], v[6:7], v[236:237]
	v_pk_add_f32 v[0:1], v[0:1], v[236:237]
	v_pk_add_f32 v[2:3], v[2:3], v[236:237]
	v_rcp_f32_e32 v0, v0
	v_rcp_f32_e32 v1, v1
	v_rcp_f32_e32 v2, v2
	v_rcp_f32_e32 v3, v3
	v_rcp_f32_e32 v4, v4
	v_rcp_f32_e32 v5, v5
	v_rcp_f32_e32 v6, v6
	v_rcp_f32_e32 v7, v7
	s_waitcnt vmcnt(12)
	v_lshlrev_b32_e32 v138, 16, v180
	v_and_b32_e32 v139, 0xffff0000, v180
	v_lshlrev_b32_e32 v140, 16, v181
	v_and_b32_e32 v141, 0xffff0000, v181
	v_lshlrev_b32_e32 v144, 16, v182
	v_and_b32_e32 v145, 0xffff0000, v182
	v_lshlrev_b32_e32 v146, 16, v183
	v_and_b32_e32 v147, 0xffff0000, v183
	v_lshlrev_b32_e32 v154, 16, v184
	v_and_b32_e32 v155, 0xffff0000, v184
	v_lshlrev_b32_e32 v156, 16, v185
	v_and_b32_e32 v157, 0xffff0000, v185
	v_lshlrev_b32_e32 v158, 16, v186
	v_and_b32_e32 v159, 0xffff0000, v186
	v_lshlrev_b32_e32 v160, 16, v187
	v_and_b32_e32 v161, 0xffff0000, v187
	v_pk_fma_f32 v[4:5], v[4:5], v[154:155], v[138:139]
	v_pk_fma_f32 v[6:7], v[6:7], v[156:157], v[140:141]
	v_pk_fma_f32 v[0:1], v[0:1], v[158:159], v[144:145]
	v_pk_fma_f32 v[2:3], v[2:3], v[160:161], v[146:147]
	global_store_dwordx4 v239, v[4:7], s[10:11] offset:512
	global_store_dwordx4 v239, v[0:3], s[10:11] offset:528
	s_branch .Lepp_done
; DI float bflo(unsigned w) { return __uint_as_float(w << 16); }
; DI float bfhi(unsigned w) { return __uint_as_float(w & 0xffff0000u); }
; DI unsigned cvt_pk_bf16(float lo, float hi) { unsigned r; asm volatile("v_cvt_pk_bf16_f32 %0, %1, %2" : "=v"(r) : "v"(lo), "v"(hi)); return r; }
; DI float sigmoidf_(float x) { return __builtin_amdgcn_rcpf(1.0f + __expf(-x)); }
;     DI void operator()(const f32x4 (&acc)[2][2][4][2], const pg8::Unit& u, int wr, int wc, int fr, int fq) const {
;         const int row0 = u.pm * 256 + wr * 64 + fr, col0 = u.pn * 256 + wc * 32 + 8 * fq;
; #pragma unroll
;         for (int ai = 0; ai < 2; ++ai)
; #pragma unroll
;             for (int m = 0; m < 4; ++m) {
;                 const size_t off = (size_t)(row0 + ai * 128 + m * 16) * D_ + col0;
; #pragma unroll
;                 for (int bj = 0; bj < 2; ++bj) {
;                     const size_t o = off + bj * 128;
;                     const f32x4 b0 = *(const f32x4*)(bg + col0 + bj * 128), b1 = *(const f32x4*)(bg + col0 + bj * 128 + 4);
;                     const u32x4 rb = *(const u32x4*)(xb + o);
;                     const u32x4 pb = *(const u32x4*)(pp + o);
;                     const f32x4 x0 = (f32x4){bflo(rb.x), bfhi(rb.x), bflo(rb.y), bfhi(rb.y)}, x1 = (f32x4){bflo(rb.z), bfhi(rb.z), bflo(rb.w), bfhi(rb.w)};
;                     const f32x4 p0 = (f32x4){bflo(pb.x), bfhi(pb.x), bflo(pb.y), bfhi(pb.y)}, p1 = (f32x4){bflo(pb.z), bfhi(pb.z), bflo(pb.w), bfhi(pb.w)};
;                     f32x4 v0, v1;
; #pragma unroll
;                     for (int j = 0; j < 4; ++j) { v0[j] = x0[j] + sigmoidf_(acc[ai][bj][m][0][j] + b0[j]) * p0[j]; v1[j] = x1[j] + sigmoidf_(acc[ai][bj][m][1][j] + b1[j]) * p1[j]; }
;                     if (out) { *(f32x4*)(out + o) = v0; *(f32x4*)(out + o + 4) = v1; }
;                     if (xbn) { u32x4 w; w.x = cvt_pk_bf16(v0[0], v0[1]); w.y = cvt_pk_bf16(v0[2], v0[3]); w.z = cvt_pk_bf16(v1[0], v1[1]); w.w = cvt_pk_bf16(v1[2], v1[3]); *(u32x4*)(xbn + o) = w; }
.Lepp_bf16:
	global_load_dwordx4 v[212:215], v244, s[8:9]
	global_load_dwordx4 v[216:219], v244, s[8:9] offset:16
	global_load_dwordx4 v[220:223], v244, s[8:9] offset:512
	global_load_dwordx4 v[224:227], v244, s[8:9] offset:528
	v_mov_b32_e32 v148, v245
	global_load_dwordx4 v[172:175], v148, s[94:95]
	global_load_dwordx4 v[176:179], v148, s[20:21]
	global_load_dwordx4 v[180:183], v148, s[94:95] offset:256
	global_load_dwordx4 v[184:187], v148, s[20:21] offset:256
	v_add_u32_e32 v149, 0x8000, v245
	global_load_dwordx4 v[188:191], v149, s[94:95]
	global_load_dwordx4 v[192:195], v149, s[20:21]
	global_load_dwordx4 v[196:199], v149, s[94:95] offset:256
	global_load_dwordx4 v[200:203], v149, s[20:21] offset:256
	v_add_u32_e32 v148, 0x10000, v245
	global_load_dwordx4 v[204:207], v148, s[94:95]
	global_load_dwordx4 v[208:211], v148, s[20:21]
	global_load_dwordx4 v[228:231], v148, s[94:95] offset:256
	global_load_dwordx4 v[232:235], v148, s[20:21] offset:256
	v_add_u32_e32 v149, 0x18000, v245
	global_load_dwordx4 v[128:131], v149, s[94:95]
	global_load_dwordx4 v[132:135], v149, s[20:21]
	s_waitcnt vmcnt(14)
	v_pk_add_f32 v[124:125], v[124:125], v[212:213]
	v_pk_add_f32 v[126:127], v[126:127], v[214:215]
	v_pk_add_f32 v[120:121], v[120:121], v[216:217]
	v_pk_add_f32 v[122:123], v[122:123], v[218:219]
	v_pk_mul_f32 v[124:125], v[124:125], v[246:247]
	v_pk_mul_f32 v[126:127], v[126:127], v[246:247]
	v_pk_mul_f32 v[120:121], v[120:121], v[246:247]
	v_pk_mul_f32 v[122:123], v[122:123], v[246:247]
	v_exp_f32_e32 v120, v120
	v_exp_f32_e32 v121, v121
	v_exp_f32_e32 v122, v122
	v_exp_f32_e32 v123, v123
	v_exp_f32_e32 v124, v124
	v_exp_f32_e32 v125, v125
	v_exp_f32_e32 v126, v126
	v_exp_f32_e32 v127, v127
	v_pk_add_f32 v[124:125], v[124:125], v[236:237]
	v_pk_add_f32 v[126:127], v[126:127], v[236:237]
	v_pk_add_f32 v[120:121], v[120:121], v[236:237]
	v_pk_add_f32 v[122:123], v[122:123], v[236:237]
	v_rcp_f32_e32 v120, v120
	v_rcp_f32_e32 v121, v121
	v_rcp_f32_e32 v122, v122
	v_rcp_f32_e32 v123, v123
	v_rcp_f32_e32 v124, v124
	v_rcp_f32_e32 v125, v125
	v_rcp_f32_e32 v126, v126
	v_rcp_f32_e32 v127, v127
	s_waitcnt vmcnt(12)
	v_lshlrev_b32_e32 v138, 16, v172
	v_and_b32_e32 v139, 0xffff0000, v172
	v_lshlrev_b32_e32 v140, 16, v173
	v_and_b32_e32 v141, 0xffff0000, v173
	v_lshlrev_b32_e32 v144, 16, v174
	v_and_b32_e32 v145, 0xffff0000, v174
	v_lshlrev_b32_e32 v146, 16, v175
	v_and_b32_e32 v147, 0xffff0000, v175
	v_lshlrev_b32_e32 v154, 16, v176
	v_and_b32_e32 v155, 0xffff0000, v176
	v_lshlrev_b32_e32 v156, 16, v177
	v_and_b32_e32 v157, 0xffff0000, v177
	v_lshlrev_b32_e32 v158, 16, v178
	v_and_b32_e32 v159, 0xffff0000, v178
	v_lshlrev_b32_e32 v160, 16, v179
	v_and_b32_e32 v161, 0xffff0000, v179
	v_pk_fma_f32 v[124:125], v[124:125], v[154:155], v[138:139]
	v_pk_fma_f32 v[126:127], v[126:127], v[156:157], v[140:141]
	v_pk_fma_f32 v[120:121], v[120:121], v[158:159], v[144:145]
	v_pk_fma_f32 v[122:123], v[122:123], v[160:161], v[146:147]
	v_mov_b32_e32 v169, v245
	v_cvt_pk_bf16_f32 v124, v124, v125
	v_cvt_pk_bf16_f32 v125, v126, v127
	v_cvt_pk_bf16_f32 v126, v120, v121
	v_cvt_pk_bf16_f32 v127, v122, v123
	global_store_dwordx4 v169, v[124:127], s[96:97]
	global_load_dwordx4 v[172:175], v149, s[94:95] offset:256
	global_load_dwordx4 v[176:179], v149, s[20:21] offset:256
	v_pk_add_f32 v[116:117], v[116:117], v[220:221]
	v_pk_add_f32 v[118:119], v[118:119], v[222:223]
	v_pk_add_f32 v[112:113], v[112:113], v[224:225]
	v_pk_add_f32 v[114:115], v[114:115], v[226:227]
	v_pk_mul_f32 v[116:117], v[116:117], v[246:247]
	v_pk_mul_f32 v[118:119], v[118:119], v[246:247]
	v_pk_mul_f32 v[112:113], v[112:113], v[246:247]
	v_pk_mul_f32 v[114:115], v[114:115], v[246:247]
	v_exp_f32_e32 v112, v112
	v_exp_f32_e32 v113, v113
	v_exp_f32_e32 v114, v114
	v_exp_f32_e32 v115, v115
	v_exp_f32_e32 v116, v116
	v_exp_f32_e32 v117, v117
	v_exp_f32_e32 v118, v118
	v_exp_f32_e32 v119, v119
	v_pk_add_f32 v[116:117], v[116:117], v[236:237]
	v_pk_add_f32 v[118:119], v[118:119], v[236:237]
	v_pk_add_f32 v[112:113], v[112:113], v[236:237]
	v_pk_add_f32 v[114:115], v[114:115], v[236:237]
	v_rcp_f32_e32 v112, v112
	v_rcp_f32_e32 v113, v113
	v_rcp_f32_e32 v114, v114
	v_rcp_f32_e32 v115, v115
	v_rcp_f32_e32 v116, v116
	v_rcp_f32_e32 v117, v117
	v_rcp_f32_e32 v118, v118
	v_rcp_f32_e32 v119, v119
	s_waitcnt vmcnt(13)
	v_lshlrev_b32_e32 v138, 16, v180
	v_and_b32_e32 v139, 0xffff0000, v180
	v_lshlrev_b32_e32 v140, 16, v181
	v_and_b32_e32 v141, 0xffff0000, v181
	v_lshlrev_b32_e32 v144, 16, v182
	v_and_b32_e32 v145, 0xffff0000, v182
	v_lshlrev_b32_e32 v146, 16, v183
	v_and_b32_e32 v147, 0xffff0000, v183
	v_lshlrev_b32_e32 v154, 16, v184
	v_and_b32_e32 v155, 0xffff0000, v184
	v_lshlrev_b32_e32 v156, 16, v185
	v_and_b32_e32 v157, 0xffff0000, v185
	v_lshlrev_b32_e32 v158, 16, v186
	v_and_b32_e32 v159, 0xffff0000, v186
	v_lshlrev_b32_e32 v160, 16, v187
	v_and_b32_e32 v161, 0xffff0000, v187
	v_pk_fma_f32 v[116:117], v[116:117], v[154:155], v[138:139]
	v_pk_fma_f32 v[118:119], v[118:119], v[156:157], v[140:141]
	v_pk_fma_f32 v[112:113], v[112:113], v[158:159], v[144:145]
	v_pk_fma_f32 v[114:115], v[114:115], v[160:161], v[146:147]
	v_cvt_pk_bf16_f32 v116, v116, v117
	v_cvt_pk_bf16_f32 v117, v118, v119
	v_cvt_pk_bf16_f32 v118, v112, v113
	v_cvt_pk_bf16_f32 v119, v114, v115
	global_store_dwordx4 v169, v[116:119], s[96:97] offset:256
	v_add_u32_e32 v148, 0x40000, v245
	global_load_dwordx4 v[180:183], v148, s[94:95]
	global_load_dwordx4 v[184:187], v148, s[20:21]
	v_pk_add_f32 v[108:109], v[108:109], v[212:213]
	v_pk_add_f32 v[110:111], v[110:111], v[214:215]
	v_pk_add_f32 v[104:105], v[104:105], v[216:217]
	v_pk_add_f32 v[106:107], v[106:107], v[218:219]
	v_pk_mul_f32 v[108:109], v[108:109], v[246:247]
	v_pk_mul_f32 v[110:111], v[110:111], v[246:247]
	v_pk_mul_f32 v[104:105], v[104:105], v[246:247]
	v_pk_mul_f32 v[106:107], v[106:107], v[246:247]
	v_exp_f32_e32 v104, v104
	v_exp_f32_e32 v105, v105
	v_exp_f32_e32 v106, v106
	v_exp_f32_e32 v107, v107
	v_exp_f32_e32 v108, v108
	v_exp_f32_e32 v109, v109
	v_exp_f32_e32 v110, v110
	v_exp_f32_e32 v111, v111
	v_pk_add_f32 v[108:109], v[108:109], v[236:237]
	v_pk_add_f32 v[110:111], v[110:111], v[236:237]
	v_pk_add_f32 v[104:105], v[104:105], v[236:237]
	v_pk_add_f32 v[106:107], v[106:107], v[236:237]
	v_rcp_f32_e32 v104, v104
	v_rcp_f32_e32 v105, v105
	v_rcp_f32_e32 v106, v106
	v_rcp_f32_e32 v107, v107
	v_rcp_f32_e32 v108, v108
	v_rcp_f32_e32 v109, v109
	v_rcp_f32_e32 v110, v110
	v_rcp_f32_e32 v111, v111
	s_waitcnt vmcnt(14)
; DI float bflo(unsigned w) { return __uint_as_float(w << 16); }
; DI float bfhi(unsigned w) { return __uint_as_float(w & 0xffff0000u); }
; DI unsigned cvt_pk_bf16(float lo, float hi) { unsigned r; asm volatile("v_cvt_pk_bf16_f32 %0, %1, %2" : "=v"(r) : "v"(lo), "v"(hi)); return r; }
; DI float sigmoidf_(float x) { return __builtin_amdgcn_rcpf(1.0f + __expf(-x)); }
;     DI void operator()(const f32x4 (&acc)[2][2][4][2], const pg8::Unit& u, int wr, int wc, int fr, int fq) const {
;         const int row0 = u.pm * 256 + wr * 64 + fr, col0 = u.pn * 256 + wc * 32 + 8 * fq;
; #pragma unroll
;         for (int ai = 0; ai < 2; ++ai)
; #pragma unroll
;             for (int m = 0; m < 4; ++m) {
;                 const size_t off = (size_t)(row0 + ai * 128 + m * 16) * D_ + col0;
; #pragma unroll
;                 for (int bj = 0; bj < 2; ++bj) {
;                     const size_t o = off + bj * 128;
;                     const f32x4 b0 = *(const f32x4*)(bg + col0 + bj * 128), b1 = *(const f32x4*)(bg + col0 + bj * 128 + 4);
;                     const u32x4 rb = *(const u32x4*)(xb + o);
;                     const u32x4 pb = *(const u32x4*)(pp + o);
;                     const f32x4 x0 = (f32x4){bflo(rb.x), bfhi(rb.x), bflo(rb.y), bfhi(rb.y)}, x1 = (f32x4){bflo(rb.z), bfhi(rb.z), bflo(rb.w), bfhi(rb.w)};
;                     const f32x4 p0 = (f32x4){bflo(pb.x), bfhi(pb.x), bflo(pb.y), bfhi(pb.y)}, p1 = (f32x4){bflo(pb.z), bfhi(pb.z), bflo(pb.w), bfhi(pb.w)};
;                     f32x4 v0, v1;
; #pragma unroll
;                     for (int j = 0; j < 4; ++j) { v0[j] = x0[j] + sigmoidf_(acc[ai][bj][m][0][j] + b0[j]) * p0[j]; v1[j] = x1[j] + sigmoidf_(acc[ai][bj][m][1][j] + b1[j]) * p1[j]; }
;                     if (out) { *(f32x4*)(out + o) = v0; *(f32x4*)(out + o + 4) = v1; }
;                     if (xbn) { u32x4 w; w.x = cvt_pk_bf16(v0[0], v0[1]); w.y = cvt_pk_bf16(v0[2], v0[3]); w.z = cvt_pk_bf16(v1[0], v1[1]); w.w = cvt_pk_bf16(v1[2], v1[3]); *(u32x4*)(xbn + o) = w; }
	v_lshlrev_b32_e32 v138, 16, v188
	v_and_b32_e32 v139, 0xffff0000, v188
	v_lshlrev_b32_e32 v140, 16, v189
	v_and_b32_e32 v141, 0xffff0000, v189
	v_lshlrev_b32_e32 v144, 16, v190
	v_and_b32_e32 v145, 0xffff0000, v190
	v_lshlrev_b32_e32 v146, 16, v191
	v_and_b32_e32 v147, 0xffff0000, v191
	v_lshlrev_b32_e32 v154, 16, v192
	v_and_b32_e32 v155, 0xffff0000, v192
	v_lshlrev_b32_e32 v156, 16, v193
	v_and_b32_e32 v157, 0xffff0000, v193
	v_lshlrev_b32_e32 v158, 16, v194
	v_and_b32_e32 v159, 0xffff0000, v194
	v_lshlrev_b32_e32 v160, 16, v195
	v_and_b32_e32 v161, 0xffff0000, v195
	v_pk_fma_f32 v[108:109], v[108:109], v[154:155], v[138:139]
	v_pk_fma_f32 v[110:111], v[110:111], v[156:157], v[140:141]
	v_pk_fma_f32 v[104:105], v[104:105], v[158:159], v[144:145]
	v_pk_fma_f32 v[106:107], v[106:107], v[160:161], v[146:147]
	v_add_u32_e32 v239, 0x8000, v245
	v_cvt_pk_bf16_f32 v108, v108, v109
	v_cvt_pk_bf16_f32 v109, v110, v111
	v_cvt_pk_bf16_f32 v110, v104, v105
	v_cvt_pk_bf16_f32 v111, v106, v107
	global_store_dwordx4 v239, v[108:111], s[96:97]
	global_load_dwordx4 v[188:191], v148, s[94:95] offset:256
	global_load_dwordx4 v[192:195], v148, s[20:21] offset:256
	v_pk_add_f32 v[100:101], v[100:101], v[220:221]
	v_pk_add_f32 v[102:103], v[102:103], v[222:223]
	v_pk_add_f32 v[96:97], v[96:97], v[224:225]
	v_pk_add_f32 v[98:99], v[98:99], v[226:227]
	v_pk_mul_f32 v[100:101], v[100:101], v[246:247]
	v_pk_mul_f32 v[102:103], v[102:103], v[246:247]
	v_pk_mul_f32 v[96:97], v[96:97], v[246:247]
	v_pk_mul_f32 v[98:99], v[98:99], v[246:247]
	v_exp_f32_e32 v96, v96
	v_exp_f32_e32 v97, v97
	v_exp_f32_e32 v98, v98
	v_exp_f32_e32 v99, v99
	v_exp_f32_e32 v100, v100
	v_exp_f32_e32 v101, v101
	v_exp_f32_e32 v102, v102
	v_exp_f32_e32 v103, v103
	v_pk_add_f32 v[100:101], v[100:101], v[236:237]
	v_pk_add_f32 v[102:103], v[102:103], v[236:237]
	v_pk_add_f32 v[96:97], v[96:97], v[236:237]
	v_pk_add_f32 v[98:99], v[98:99], v[236:237]
	v_rcp_f32_e32 v96, v96
	v_rcp_f32_e32 v97, v97
	v_rcp_f32_e32 v98, v98
	v_rcp_f32_e32 v99, v99
	v_rcp_f32_e32 v100, v100
	v_rcp_f32_e32 v101, v101
	v_rcp_f32_e32 v102, v102
	v_rcp_f32_e32 v103, v103
	s_waitcnt vmcnt(15)
	v_lshlrev_b32_e32 v138, 16, v196
	v_and_b32_e32 v139, 0xffff0000, v196
	v_lshlrev_b32_e32 v140, 16, v197
	v_and_b32_e32 v141, 0xffff0000, v197
	v_lshlrev_b32_e32 v144, 16, v198
	v_and_b32_e32 v145, 0xffff0000, v198
	v_lshlrev_b32_e32 v146, 16, v199
	v_and_b32_e32 v147, 0xffff0000, v199
	v_lshlrev_b32_e32 v154, 16, v200
	v_and_b32_e32 v155, 0xffff0000, v200
	v_lshlrev_b32_e32 v156, 16, v201
	v_and_b32_e32 v157, 0xffff0000, v201
	v_lshlrev_b32_e32 v158, 16, v202
	v_and_b32_e32 v159, 0xffff0000, v202
	v_lshlrev_b32_e32 v160, 16, v203
	v_and_b32_e32 v161, 0xffff0000, v203
	v_pk_fma_f32 v[100:101], v[100:101], v[154:155], v[138:139]
	v_pk_fma_f32 v[102:103], v[102:103], v[156:157], v[140:141]
	v_pk_fma_f32 v[96:97], v[96:97], v[158:159], v[144:145]
	v_pk_fma_f32 v[98:99], v[98:99], v[160:161], v[146:147]
	v_cvt_pk_bf16_f32 v100, v100, v101
	v_cvt_pk_bf16_f32 v101, v102, v103
	v_cvt_pk_bf16_f32 v102, v96, v97
	v_cvt_pk_bf16_f32 v103, v98, v99
	global_store_dwordx4 v239, v[100:103], s[96:97] offset:256
	v_add_u32_e32 v149, 0x48000, v245
	global_load_dwordx4 v[196:199], v149, s[94:95]
	global_load_dwordx4 v[200:203], v149, s[20:21]
	v_pk_add_f32 v[92:93], v[92:93], v[212:213]
	v_pk_add_f32 v[94:95], v[94:95], v[214:215]
	v_pk_add_f32 v[88:89], v[88:89], v[216:217]
	v_pk_add_f32 v[90:91], v[90:91], v[218:219]
	v_pk_mul_f32 v[92:93], v[92:93], v[246:247]
	v_pk_mul_f32 v[94:95], v[94:95], v[246:247]
	v_pk_mul_f32 v[88:89], v[88:89], v[246:247]
	v_pk_mul_f32 v[90:91], v[90:91], v[246:247]
	v_exp_f32_e32 v88, v88
	v_exp_f32_e32 v89, v89
	v_exp_f32_e32 v90, v90
	v_exp_f32_e32 v91, v91
	v_exp_f32_e32 v92, v92
	v_exp_f32_e32 v93, v93
	v_exp_f32_e32 v94, v94
	v_exp_f32_e32 v95, v95
	v_pk_add_f32 v[92:93], v[92:93], v[236:237]
	v_pk_add_f32 v[94:95], v[94:95], v[236:237]
	v_pk_add_f32 v[88:89], v[88:89], v[236:237]
	v_pk_add_f32 v[90:91], v[90:91], v[236:237]
	v_rcp_f32_e32 v88, v88
	v_rcp_f32_e32 v89, v89
	v_rcp_f32_e32 v90, v90
	v_rcp_f32_e32 v91, v91
	v_rcp_f32_e32 v92, v92
	v_rcp_f32_e32 v93, v93
	v_rcp_f32_e32 v94, v94
	v_rcp_f32_e32 v95, v95
	s_waitcnt vmcnt(16)
	v_lshlrev_b32_e32 v138, 16, v204
	v_and_b32_e32 v139, 0xffff0000, v204
	v_lshlrev_b32_e32 v140, 16, v205
	v_and_b32_e32 v141, 0xffff0000, v205
	v_lshlrev_b32_e32 v144, 16, v206
	v_and_b32_e32 v145, 0xffff0000, v206
	v_lshlrev_b32_e32 v146, 16, v207
	v_and_b32_e32 v147, 0xffff0000, v207
	v_lshlrev_b32_e32 v154, 16, v208
	v_and_b32_e32 v155, 0xffff0000, v208
	v_lshlrev_b32_e32 v156, 16, v209
	v_and_b32_e32 v157, 0xffff0000, v209
	v_lshlrev_b32_e32 v158, 16, v210
	v_and_b32_e32 v159, 0xffff0000, v210
	v_lshlrev_b32_e32 v160, 16, v211
	v_and_b32_e32 v161, 0xffff0000, v211
	v_pk_fma_f32 v[92:93], v[92:93], v[154:155], v[138:139]
	v_pk_fma_f32 v[94:95], v[94:95], v[156:157], v[140:141]
	v_pk_fma_f32 v[88:89], v[88:89], v[158:159], v[144:145]
	v_pk_fma_f32 v[90:91], v[90:91], v[160:161], v[146:147]
	v_add_u32_e32 v169, 0x10000, v245
	v_cvt_pk_bf16_f32 v92, v92, v93
	v_cvt_pk_bf16_f32 v93, v94, v95
	v_cvt_pk_bf16_f32 v94, v88, v89
	v_cvt_pk_bf16_f32 v95, v90, v91
	global_store_dwordx4 v169, v[92:95], s[96:97]
	global_load_dwordx4 v[204:207], v149, s[94:95] offset:256
	global_load_dwordx4 v[208:211], v149, s[20:21] offset:256
	v_pk_add_f32 v[84:85], v[84:85], v[220:221]
	v_pk_add_f32 v[86:87], v[86:87], v[222:223]
	v_pk_add_f32 v[80:81], v[80:81], v[224:225]
	v_pk_add_f32 v[82:83], v[82:83], v[226:227]
	v_pk_mul_f32 v[84:85], v[84:85], v[246:247]
	v_pk_mul_f32 v[86:87], v[86:87], v[246:247]
	v_pk_mul_f32 v[80:81], v[80:81], v[246:247]
	v_pk_mul_f32 v[82:83], v[82:83], v[246:247]
	v_exp_f32_e32 v80, v80
	v_exp_f32_e32 v81, v81
	v_exp_f32_e32 v82, v82
	v_exp_f32_e32 v83, v83
	v_exp_f32_e32 v84, v84
	v_exp_f32_e32 v85, v85
	v_exp_f32_e32 v86, v86
	v_exp_f32_e32 v87, v87
	v_pk_add_f32 v[84:85], v[84:85], v[236:237]
	v_pk_add_f32 v[86:87], v[86:87], v[236:237]
	v_pk_add_f32 v[80:81], v[80:81], v[236:237]
	v_pk_add_f32 v[82:83], v[82:83], v[236:237]
	v_rcp_f32_e32 v80, v80
	v_rcp_f32_e32 v81, v81
	v_rcp_f32_e32 v82, v82
	v_rcp_f32_e32 v83, v83
	v_rcp_f32_e32 v84, v84
	v_rcp_f32_e32 v85, v85
	v_rcp_f32_e32 v86, v86
	v_rcp_f32_e32 v87, v87
	s_waitcnt vmcnt(17)
; DI float bflo(unsigned w) { return __uint_as_float(w << 16); }
; DI float bfhi(unsigned w) { return __uint_as_float(w & 0xffff0000u); }
; DI unsigned cvt_pk_bf16(float lo, float hi) { unsigned r; asm volatile("v_cvt_pk_bf16_f32 %0, %1, %2" : "=v"(r) : "v"(lo), "v"(hi)); return r; }
; DI float sigmoidf_(float x) { return __builtin_amdgcn_rcpf(1.0f + __expf(-x)); }
;     DI void operator()(const f32x4 (&acc)[2][2][4][2], const pg8::Unit& u, int wr, int wc, int fr, int fq) const {
;         const int row0 = u.pm * 256 + wr * 64 + fr, col0 = u.pn * 256 + wc * 32 + 8 * fq;
; #pragma unroll
;         for (int ai = 0; ai < 2; ++ai)
; #pragma unroll
;             for (int m = 0; m < 4; ++m) {
;                 const size_t off = (size_t)(row0 + ai * 128 + m * 16) * D_ + col0;
; #pragma unroll
;                 for (int bj = 0; bj < 2; ++bj) {
;                     const size_t o = off + bj * 128;
;                     const f32x4 b0 = *(const f32x4*)(bg + col0 + bj * 128), b1 = *(const f32x4*)(bg + col0 + bj * 128 + 4);
;                     const u32x4 rb = *(const u32x4*)(xb + o);
;                     const u32x4 pb = *(const u32x4*)(pp + o);
;                     const f32x4 x0 = (f32x4){bflo(rb.x), bfhi(rb.x), bflo(rb.y), bfhi(rb.y)}, x1 = (f32x4){bflo(rb.z), bfhi(rb.z), bflo(rb.w), bfhi(rb.w)};
;                     const f32x4 p0 = (f32x4){bflo(pb.x), bfhi(pb.x), bflo(pb.y), bfhi(pb.y)}, p1 = (f32x4){bflo(pb.z), bfhi(pb.z), bflo(pb.w), bfhi(pb.w)};
;                     f32x4 v0, v1;
; #pragma unroll
;                     for (int j = 0; j < 4; ++j) { v0[j] = x0[j] + sigmoidf_(acc[ai][bj][m][0][j] + b0[j]) * p0[j]; v1[j] = x1[j] + sigmoidf_(acc[ai][bj][m][1][j] + b1[j]) * p1[j]; }
;                     if (out) { *(f32x4*)(out + o) = v0; *(f32x4*)(out + o + 4) = v1; }
;                     if (xbn) { u32x4 w; w.x = cvt_pk_bf16(v0[0], v0[1]); w.y = cvt_pk_bf16(v0[2], v0[3]); w.z = cvt_pk_bf16(v1[0], v1[1]); w.w = cvt_pk_bf16(v1[2], v1[3]); *(u32x4*)(xbn + o) = w; }
	v_lshlrev_b32_e32 v138, 16, v228
	v_and_b32_e32 v139, 0xffff0000, v228
	v_lshlrev_b32_e32 v140, 16, v229
	v_and_b32_e32 v141, 0xffff0000, v229
	v_lshlrev_b32_e32 v144, 16, v230
	v_and_b32_e32 v145, 0xffff0000, v230
	v_lshlrev_b32_e32 v146, 16, v231
	v_and_b32_e32 v147, 0xffff0000, v231
	v_lshlrev_b32_e32 v154, 16, v232
	v_and_b32_e32 v155, 0xffff0000, v232
	v_lshlrev_b32_e32 v156, 16, v233
	v_and_b32_e32 v157, 0xffff0000, v233
	v_lshlrev_b32_e32 v158, 16, v234
	v_and_b32_e32 v159, 0xffff0000, v234
	v_lshlrev_b32_e32 v160, 16, v235
	v_and_b32_e32 v161, 0xffff0000, v235
	v_pk_fma_f32 v[84:85], v[84:85], v[154:155], v[138:139]
	v_pk_fma_f32 v[86:87], v[86:87], v[156:157], v[140:141]
	v_pk_fma_f32 v[80:81], v[80:81], v[158:159], v[144:145]
	v_pk_fma_f32 v[82:83], v[82:83], v[160:161], v[146:147]
	v_cvt_pk_bf16_f32 v84, v84, v85
	v_cvt_pk_bf16_f32 v85, v86, v87
	v_cvt_pk_bf16_f32 v86, v80, v81
	v_cvt_pk_bf16_f32 v87, v82, v83
	global_store_dwordx4 v169, v[84:87], s[96:97] offset:256
	v_add_u32_e32 v148, 0x50000, v245
	global_load_dwordx4 v[228:231], v148, s[94:95]
	global_load_dwordx4 v[232:235], v148, s[20:21]
	v_pk_add_f32 v[76:77], v[76:77], v[212:213]
	v_pk_add_f32 v[78:79], v[78:79], v[214:215]
	v_pk_add_f32 v[72:73], v[72:73], v[216:217]
	v_pk_add_f32 v[74:75], v[74:75], v[218:219]
	v_pk_mul_f32 v[76:77], v[76:77], v[246:247]
	v_pk_mul_f32 v[78:79], v[78:79], v[246:247]
	v_pk_mul_f32 v[72:73], v[72:73], v[246:247]
	v_pk_mul_f32 v[74:75], v[74:75], v[246:247]
	v_exp_f32_e32 v72, v72
	v_exp_f32_e32 v73, v73
	v_exp_f32_e32 v74, v74
	v_exp_f32_e32 v75, v75
	v_exp_f32_e32 v76, v76
	v_exp_f32_e32 v77, v77
	v_exp_f32_e32 v78, v78
	v_exp_f32_e32 v79, v79
	v_pk_add_f32 v[76:77], v[76:77], v[236:237]
	v_pk_add_f32 v[78:79], v[78:79], v[236:237]
	v_pk_add_f32 v[72:73], v[72:73], v[236:237]
	v_pk_add_f32 v[74:75], v[74:75], v[236:237]
	v_rcp_f32_e32 v72, v72
	v_rcp_f32_e32 v73, v73
	v_rcp_f32_e32 v74, v74
	v_rcp_f32_e32 v75, v75
	v_rcp_f32_e32 v76, v76
	v_rcp_f32_e32 v77, v77
	v_rcp_f32_e32 v78, v78
	v_rcp_f32_e32 v79, v79
	s_waitcnt vmcnt(18)
	v_lshlrev_b32_e32 v138, 16, v128
	v_and_b32_e32 v139, 0xffff0000, v128
	v_lshlrev_b32_e32 v140, 16, v129
	v_and_b32_e32 v141, 0xffff0000, v129
	v_lshlrev_b32_e32 v144, 16, v130
	v_and_b32_e32 v145, 0xffff0000, v130
	v_lshlrev_b32_e32 v146, 16, v131
	v_and_b32_e32 v147, 0xffff0000, v131
	v_lshlrev_b32_e32 v154, 16, v132
	v_and_b32_e32 v155, 0xffff0000, v132
	v_lshlrev_b32_e32 v156, 16, v133
	v_and_b32_e32 v157, 0xffff0000, v133
	v_lshlrev_b32_e32 v158, 16, v134
	v_and_b32_e32 v159, 0xffff0000, v134
	v_lshlrev_b32_e32 v160, 16, v135
	v_and_b32_e32 v161, 0xffff0000, v135
	v_pk_fma_f32 v[76:77], v[76:77], v[154:155], v[138:139]
	v_pk_fma_f32 v[78:79], v[78:79], v[156:157], v[140:141]
	v_pk_fma_f32 v[72:73], v[72:73], v[158:159], v[144:145]
	v_pk_fma_f32 v[74:75], v[74:75], v[160:161], v[146:147]
	v_add_u32_e32 v239, 0x18000, v245
	v_cvt_pk_bf16_f32 v76, v76, v77
	v_cvt_pk_bf16_f32 v77, v78, v79
	v_cvt_pk_bf16_f32 v78, v72, v73
	v_cvt_pk_bf16_f32 v79, v74, v75
	global_store_dwordx4 v239, v[76:79], s[96:97]
	global_load_dwordx4 v[128:131], v148, s[94:95] offset:256
	global_load_dwordx4 v[132:135], v148, s[20:21] offset:256
	v_pk_add_f32 v[68:69], v[68:69], v[220:221]
	v_pk_add_f32 v[70:71], v[70:71], v[222:223]
	v_pk_add_f32 v[64:65], v[64:65], v[224:225]
	v_pk_add_f32 v[66:67], v[66:67], v[226:227]
	v_pk_mul_f32 v[68:69], v[68:69], v[246:247]
	v_pk_mul_f32 v[70:71], v[70:71], v[246:247]
	v_pk_mul_f32 v[64:65], v[64:65], v[246:247]
	v_pk_mul_f32 v[66:67], v[66:67], v[246:247]
	v_exp_f32_e32 v64, v64
	v_exp_f32_e32 v65, v65
	v_exp_f32_e32 v66, v66
	v_exp_f32_e32 v67, v67
	v_exp_f32_e32 v68, v68
	v_exp_f32_e32 v69, v69
	v_exp_f32_e32 v70, v70
	v_exp_f32_e32 v71, v71
	v_pk_add_f32 v[68:69], v[68:69], v[236:237]
	v_pk_add_f32 v[70:71], v[70:71], v[236:237]
	v_pk_add_f32 v[64:65], v[64:65], v[236:237]
	v_pk_add_f32 v[66:67], v[66:67], v[236:237]
	v_rcp_f32_e32 v64, v64
	v_rcp_f32_e32 v65, v65
	v_rcp_f32_e32 v66, v66
	v_rcp_f32_e32 v67, v67
	v_rcp_f32_e32 v68, v68
	v_rcp_f32_e32 v69, v69
	v_rcp_f32_e32 v70, v70
	v_rcp_f32_e32 v71, v71
	s_waitcnt vmcnt(18)
	v_lshlrev_b32_e32 v138, 16, v172
	v_and_b32_e32 v139, 0xffff0000, v172
	v_lshlrev_b32_e32 v140, 16, v173
	v_and_b32_e32 v141, 0xffff0000, v173
	v_lshlrev_b32_e32 v144, 16, v174
	v_and_b32_e32 v145, 0xffff0000, v174
	v_lshlrev_b32_e32 v146, 16, v175
	v_and_b32_e32 v147, 0xffff0000, v175
	v_lshlrev_b32_e32 v154, 16, v176
	v_and_b32_e32 v155, 0xffff0000, v176
	v_lshlrev_b32_e32 v156, 16, v177
	v_and_b32_e32 v157, 0xffff0000, v177
	v_lshlrev_b32_e32 v158, 16, v178
	v_and_b32_e32 v159, 0xffff0000, v178
	v_lshlrev_b32_e32 v160, 16, v179
	v_and_b32_e32 v161, 0xffff0000, v179
	v_pk_fma_f32 v[68:69], v[68:69], v[154:155], v[138:139]
	v_pk_fma_f32 v[70:71], v[70:71], v[156:157], v[140:141]
	v_pk_fma_f32 v[64:65], v[64:65], v[158:159], v[144:145]
	v_pk_fma_f32 v[66:67], v[66:67], v[160:161], v[146:147]
	v_cvt_pk_bf16_f32 v68, v68, v69
	v_cvt_pk_bf16_f32 v69, v70, v71
	v_cvt_pk_bf16_f32 v70, v64, v65
	v_cvt_pk_bf16_f32 v71, v66, v67
	global_store_dwordx4 v239, v[68:71], s[96:97] offset:256
	v_add_u32_e32 v149, 0x58000, v245
	global_load_dwordx4 v[172:175], v149, s[94:95]
	global_load_dwordx4 v[176:179], v149, s[20:21]
	v_pk_add_f32 v[60:61], v[60:61], v[212:213]
	v_pk_add_f32 v[62:63], v[62:63], v[214:215]
	v_pk_add_f32 v[56:57], v[56:57], v[216:217]
	v_pk_add_f32 v[58:59], v[58:59], v[218:219]
	v_pk_mul_f32 v[60:61], v[60:61], v[246:247]
	v_pk_mul_f32 v[62:63], v[62:63], v[246:247]
	v_pk_mul_f32 v[56:57], v[56:57], v[246:247]
	v_pk_mul_f32 v[58:59], v[58:59], v[246:247]
	v_exp_f32_e32 v56, v56
	v_exp_f32_e32 v57, v57
	v_exp_f32_e32 v58, v58
	v_exp_f32_e32 v59, v59
	v_exp_f32_e32 v60, v60
	v_exp_f32_e32 v61, v61
	v_exp_f32_e32 v62, v62
	v_exp_f32_e32 v63, v63
	v_pk_add_f32 v[60:61], v[60:61], v[236:237]
	v_pk_add_f32 v[62:63], v[62:63], v[236:237]
	v_pk_add_f32 v[56:57], v[56:57], v[236:237]
	v_pk_add_f32 v[58:59], v[58:59], v[236:237]
	v_rcp_f32_e32 v56, v56
	v_rcp_f32_e32 v57, v57
	v_rcp_f32_e32 v58, v58
	v_rcp_f32_e32 v59, v59
	v_rcp_f32_e32 v60, v60
	v_rcp_f32_e32 v61, v61
	v_rcp_f32_e32 v62, v62
	v_rcp_f32_e32 v63, v63
	s_waitcnt vmcnt(18)
; DI float bflo(unsigned w) { return __uint_as_float(w << 16); }
; DI float bfhi(unsigned w) { return __uint_as_float(w & 0xffff0000u); }
; DI unsigned cvt_pk_bf16(float lo, float hi) { unsigned r; asm volatile("v_cvt_pk_bf16_f32 %0, %1, %2" : "=v"(r) : "v"(lo), "v"(hi)); return r; }
; DI float sigmoidf_(float x) { return __builtin_amdgcn_rcpf(1.0f + __expf(-x)); }
;     DI void operator()(const f32x4 (&acc)[2][2][4][2], const pg8::Unit& u, int wr, int wc, int fr, int fq) const {
;         const int row0 = u.pm * 256 + wr * 64 + fr, col0 = u.pn * 256 + wc * 32 + 8 * fq;
; #pragma unroll
;         for (int ai = 0; ai < 2; ++ai)
; #pragma unroll
;             for (int m = 0; m < 4; ++m) {
;                 const size_t off = (size_t)(row0 + ai * 128 + m * 16) * D_ + col0;
; #pragma unroll
;                 for (int bj = 0; bj < 2; ++bj) {
;                     const size_t o = off + bj * 128;
;                     const f32x4 b0 = *(const f32x4*)(bg + col0 + bj * 128), b1 = *(const f32x4*)(bg + col0 + bj * 128 + 4);
;                     const u32x4 rb = *(const u32x4*)(xb + o);
;                     const u32x4 pb = *(const u32x4*)(pp + o);
;                     const f32x4 x0 = (f32x4){bflo(rb.x), bfhi(rb.x), bflo(rb.y), bfhi(rb.y)}, x1 = (f32x4){bflo(rb.z), bfhi(rb.z), bflo(rb.w), bfhi(rb.w)};
;                     const f32x4 p0 = (f32x4){bflo(pb.x), bfhi(pb.x), bflo(pb.y), bfhi(pb.y)}, p1 = (f32x4){bflo(pb.z), bfhi(pb.z), bflo(pb.w), bfhi(pb.w)};
;                     f32x4 v0, v1;
; #pragma unroll
;                     for (int j = 0; j < 4; ++j) { v0[j] = x0[j] + sigmoidf_(acc[ai][bj][m][0][j] + b0[j]) * p0[j]; v1[j] = x1[j] + sigmoidf_(acc[ai][bj][m][1][j] + b1[j]) * p1[j]; }
;                     if (out) { *(f32x4*)(out + o) = v0; *(f32x4*)(out + o + 4) = v1; }
;                     if (xbn) { u32x4 w; w.x = cvt_pk_bf16(v0[0], v0[1]); w.y = cvt_pk_bf16(v0[2], v0[3]); w.z = cvt_pk_bf16(v1[0], v1[1]); w.w = cvt_pk_bf16(v1[2], v1[3]); *(u32x4*)(xbn + o) = w; }
	v_lshlrev_b32_e32 v138, 16, v180
	v_and_b32_e32 v139, 0xffff0000, v180
	v_lshlrev_b32_e32 v140, 16, v181
	v_and_b32_e32 v141, 0xffff0000, v181
	v_lshlrev_b32_e32 v144, 16, v182
	v_and_b32_e32 v145, 0xffff0000, v182
	v_lshlrev_b32_e32 v146, 16, v183
	v_and_b32_e32 v147, 0xffff0000, v183
	v_lshlrev_b32_e32 v154, 16, v184
	v_and_b32_e32 v155, 0xffff0000, v184
	v_lshlrev_b32_e32 v156, 16, v185
	v_and_b32_e32 v157, 0xffff0000, v185
	v_lshlrev_b32_e32 v158, 16, v186
	v_and_b32_e32 v159, 0xffff0000, v186
	v_lshlrev_b32_e32 v160, 16, v187
	v_and_b32_e32 v161, 0xffff0000, v187
	v_pk_fma_f32 v[60:61], v[60:61], v[154:155], v[138:139]
	v_pk_fma_f32 v[62:63], v[62:63], v[156:157], v[140:141]
	v_pk_fma_f32 v[56:57], v[56:57], v[158:159], v[144:145]
	v_pk_fma_f32 v[58:59], v[58:59], v[160:161], v[146:147]
	v_add_u32_e32 v169, 0x40000, v245
	v_cvt_pk_bf16_f32 v60, v60, v61
	v_cvt_pk_bf16_f32 v61, v62, v63
	v_cvt_pk_bf16_f32 v62, v56, v57
	v_cvt_pk_bf16_f32 v63, v58, v59
	global_store_dwordx4 v169, v[60:63], s[96:97]
	global_load_dwordx4 v[180:183], v149, s[94:95] offset:256
	global_load_dwordx4 v[184:187], v149, s[20:21] offset:256
	v_pk_add_f32 v[52:53], v[52:53], v[220:221]
	v_pk_add_f32 v[54:55], v[54:55], v[222:223]
	v_pk_add_f32 v[48:49], v[48:49], v[224:225]
	v_pk_add_f32 v[50:51], v[50:51], v[226:227]
	v_pk_mul_f32 v[52:53], v[52:53], v[246:247]
	v_pk_mul_f32 v[54:55], v[54:55], v[246:247]
	v_pk_mul_f32 v[48:49], v[48:49], v[246:247]
	v_pk_mul_f32 v[50:51], v[50:51], v[246:247]
	v_exp_f32_e32 v48, v48
	v_exp_f32_e32 v49, v49
	v_exp_f32_e32 v50, v50
	v_exp_f32_e32 v51, v51
	v_exp_f32_e32 v52, v52
	v_exp_f32_e32 v53, v53
	v_exp_f32_e32 v54, v54
	v_exp_f32_e32 v55, v55
	v_pk_add_f32 v[52:53], v[52:53], v[236:237]
	v_pk_add_f32 v[54:55], v[54:55], v[236:237]
	v_pk_add_f32 v[48:49], v[48:49], v[236:237]
	v_pk_add_f32 v[50:51], v[50:51], v[236:237]
	v_rcp_f32_e32 v48, v48
	v_rcp_f32_e32 v49, v49
	v_rcp_f32_e32 v50, v50
	v_rcp_f32_e32 v51, v51
	v_rcp_f32_e32 v52, v52
	v_rcp_f32_e32 v53, v53
	v_rcp_f32_e32 v54, v54
	v_rcp_f32_e32 v55, v55
	s_waitcnt vmcnt(18)
	v_lshlrev_b32_e32 v138, 16, v188
	v_and_b32_e32 v139, 0xffff0000, v188
	v_lshlrev_b32_e32 v140, 16, v189
	v_and_b32_e32 v141, 0xffff0000, v189
	v_lshlrev_b32_e32 v144, 16, v190
	v_and_b32_e32 v145, 0xffff0000, v190
	v_lshlrev_b32_e32 v146, 16, v191
	v_and_b32_e32 v147, 0xffff0000, v191
	v_lshlrev_b32_e32 v154, 16, v192
	v_and_b32_e32 v155, 0xffff0000, v192
	v_lshlrev_b32_e32 v156, 16, v193
	v_and_b32_e32 v157, 0xffff0000, v193
	v_lshlrev_b32_e32 v158, 16, v194
	v_and_b32_e32 v159, 0xffff0000, v194
	v_lshlrev_b32_e32 v160, 16, v195
	v_and_b32_e32 v161, 0xffff0000, v195
	v_pk_fma_f32 v[52:53], v[52:53], v[154:155], v[138:139]
	v_pk_fma_f32 v[54:55], v[54:55], v[156:157], v[140:141]
	v_pk_fma_f32 v[48:49], v[48:49], v[158:159], v[144:145]
	v_pk_fma_f32 v[50:51], v[50:51], v[160:161], v[146:147]
	v_cvt_pk_bf16_f32 v52, v52, v53
	v_cvt_pk_bf16_f32 v53, v54, v55
	v_cvt_pk_bf16_f32 v54, v48, v49
	v_cvt_pk_bf16_f32 v55, v50, v51
	global_store_dwordx4 v169, v[52:55], s[96:97] offset:256
	v_pk_add_f32 v[44:45], v[44:45], v[212:213]
	v_pk_add_f32 v[46:47], v[46:47], v[214:215]
	v_pk_add_f32 v[40:41], v[40:41], v[216:217]
	v_pk_add_f32 v[42:43], v[42:43], v[218:219]
	v_pk_mul_f32 v[44:45], v[44:45], v[246:247]
	v_pk_mul_f32 v[46:47], v[46:47], v[246:247]
	v_pk_mul_f32 v[40:41], v[40:41], v[246:247]
	v_pk_mul_f32 v[42:43], v[42:43], v[246:247]
	v_exp_f32_e32 v40, v40
	v_exp_f32_e32 v41, v41
	v_exp_f32_e32 v42, v42
	v_exp_f32_e32 v43, v43
	v_exp_f32_e32 v44, v44
	v_exp_f32_e32 v45, v45
	v_exp_f32_e32 v46, v46
	v_exp_f32_e32 v47, v47
	v_pk_add_f32 v[44:45], v[44:45], v[236:237]
	v_pk_add_f32 v[46:47], v[46:47], v[236:237]
	v_pk_add_f32 v[40:41], v[40:41], v[236:237]
	v_pk_add_f32 v[42:43], v[42:43], v[236:237]
	v_rcp_f32_e32 v40, v40
	v_rcp_f32_e32 v41, v41
	v_rcp_f32_e32 v42, v42
	v_rcp_f32_e32 v43, v43
	v_rcp_f32_e32 v44, v44
	v_rcp_f32_e32 v45, v45
	v_rcp_f32_e32 v46, v46
	v_rcp_f32_e32 v47, v47
	s_waitcnt vmcnt(16)
	v_lshlrev_b32_e32 v138, 16, v196
	v_and_b32_e32 v139, 0xffff0000, v196
	v_lshlrev_b32_e32 v140, 16, v197
	v_and_b32_e32 v141, 0xffff0000, v197
	v_lshlrev_b32_e32 v144, 16, v198
	v_and_b32_e32 v145, 0xffff0000, v198
	v_lshlrev_b32_e32 v146, 16, v199
	v_and_b32_e32 v147, 0xffff0000, v199
	v_lshlrev_b32_e32 v154, 16, v200
	v_and_b32_e32 v155, 0xffff0000, v200
	v_lshlrev_b32_e32 v156, 16, v201
	v_and_b32_e32 v157, 0xffff0000, v201
	v_lshlrev_b32_e32 v158, 16, v202
	v_and_b32_e32 v159, 0xffff0000, v202
	v_lshlrev_b32_e32 v160, 16, v203
	v_and_b32_e32 v161, 0xffff0000, v203
	v_pk_fma_f32 v[44:45], v[44:45], v[154:155], v[138:139]
	v_pk_fma_f32 v[46:47], v[46:47], v[156:157], v[140:141]
	v_pk_fma_f32 v[40:41], v[40:41], v[158:159], v[144:145]
	v_pk_fma_f32 v[42:43], v[42:43], v[160:161], v[146:147]
	v_add_u32_e32 v239, 0x48000, v245
	v_cvt_pk_bf16_f32 v44, v44, v45
	v_cvt_pk_bf16_f32 v45, v46, v47
	v_cvt_pk_bf16_f32 v46, v40, v41
	v_cvt_pk_bf16_f32 v47, v42, v43
	global_store_dwordx4 v239, v[44:47], s[96:97]
	v_pk_add_f32 v[36:37], v[36:37], v[220:221]
	v_pk_add_f32 v[38:39], v[38:39], v[222:223]
	v_pk_add_f32 v[32:33], v[32:33], v[224:225]
	v_pk_add_f32 v[34:35], v[34:35], v[226:227]
	v_pk_mul_f32 v[36:37], v[36:37], v[246:247]
	v_pk_mul_f32 v[38:39], v[38:39], v[246:247]
	v_pk_mul_f32 v[32:33], v[32:33], v[246:247]
	v_pk_mul_f32 v[34:35], v[34:35], v[246:247]
	v_exp_f32_e32 v32, v32
	v_exp_f32_e32 v33, v33
	v_exp_f32_e32 v34, v34
	v_exp_f32_e32 v35, v35
	v_exp_f32_e32 v36, v36
	v_exp_f32_e32 v37, v37
	v_exp_f32_e32 v38, v38
	v_exp_f32_e32 v39, v39
	v_pk_add_f32 v[36:37], v[36:37], v[236:237]
	v_pk_add_f32 v[38:39], v[38:39], v[236:237]
	v_pk_add_f32 v[32:33], v[32:33], v[236:237]
	v_pk_add_f32 v[34:35], v[34:35], v[236:237]
	v_rcp_f32_e32 v32, v32
	v_rcp_f32_e32 v33, v33
	v_rcp_f32_e32 v34, v34
	v_rcp_f32_e32 v35, v35
	v_rcp_f32_e32 v36, v36
	v_rcp_f32_e32 v37, v37
	v_rcp_f32_e32 v38, v38
	v_rcp_f32_e32 v39, v39
	s_waitcnt vmcnt(14)
; DI float bflo(unsigned w) { return __uint_as_float(w << 16); }
; DI float bfhi(unsigned w) { return __uint_as_float(w & 0xffff0000u); }
; DI unsigned cvt_pk_bf16(float lo, float hi) { unsigned r; asm volatile("v_cvt_pk_bf16_f32 %0, %1, %2" : "=v"(r) : "v"(lo), "v"(hi)); return r; }
; DI float sigmoidf_(float x) { return __builtin_amdgcn_rcpf(1.0f + __expf(-x)); }
;     DI void operator()(const f32x4 (&acc)[2][2][4][2], const pg8::Unit& u, int wr, int wc, int fr, int fq) const {
;         const int row0 = u.pm * 256 + wr * 64 + fr, col0 = u.pn * 256 + wc * 32 + 8 * fq;
; #pragma unroll
;         for (int ai = 0; ai < 2; ++ai)
; #pragma unroll
;             for (int m = 0; m < 4; ++m) {
;                 const size_t off = (size_t)(row0 + ai * 128 + m * 16) * D_ + col0;
; #pragma unroll
;                 for (int bj = 0; bj < 2; ++bj) {
;                     const size_t o = off + bj * 128;
;                     const f32x4 b0 = *(const f32x4*)(bg + col0 + bj * 128), b1 = *(const f32x4*)(bg + col0 + bj * 128 + 4);
;                     const u32x4 rb = *(const u32x4*)(xb + o);
;                     const u32x4 pb = *(const u32x4*)(pp + o);
;                     const f32x4 x0 = (f32x4){bflo(rb.x), bfhi(rb.x), bflo(rb.y), bfhi(rb.y)}, x1 = (f32x4){bflo(rb.z), bfhi(rb.z), bflo(rb.w), bfhi(rb.w)};
;                     const f32x4 p0 = (f32x4){bflo(pb.x), bfhi(pb.x), bflo(pb.y), bfhi(pb.y)}, p1 = (f32x4){bflo(pb.z), bfhi(pb.z), bflo(pb.w), bfhi(pb.w)};
;                     f32x4 v0, v1;
; #pragma unroll
;                     for (int j = 0; j < 4; ++j) { v0[j] = x0[j] + sigmoidf_(acc[ai][bj][m][0][j] + b0[j]) * p0[j]; v1[j] = x1[j] + sigmoidf_(acc[ai][bj][m][1][j] + b1[j]) * p1[j]; }
;                     if (out) { *(f32x4*)(out + o) = v0; *(f32x4*)(out + o + 4) = v1; }
;                     if (xbn) { u32x4 w; w.x = cvt_pk_bf16(v0[0], v0[1]); w.y = cvt_pk_bf16(v0[2], v0[3]); w.z = cvt_pk_bf16(v1[0], v1[1]); w.w = cvt_pk_bf16(v1[2], v1[3]); *(u32x4*)(xbn + o) = w; }
	v_lshlrev_b32_e32 v138, 16, v204
	v_and_b32_e32 v139, 0xffff0000, v204
	v_lshlrev_b32_e32 v140, 16, v205
	v_and_b32_e32 v141, 0xffff0000, v205
	v_lshlrev_b32_e32 v144, 16, v206
	v_and_b32_e32 v145, 0xffff0000, v206
	v_lshlrev_b32_e32 v146, 16, v207
	v_and_b32_e32 v147, 0xffff0000, v207
	v_lshlrev_b32_e32 v154, 16, v208
	v_and_b32_e32 v155, 0xffff0000, v208
	v_lshlrev_b32_e32 v156, 16, v209
	v_and_b32_e32 v157, 0xffff0000, v209
	v_lshlrev_b32_e32 v158, 16, v210
	v_and_b32_e32 v159, 0xffff0000, v210
	v_lshlrev_b32_e32 v160, 16, v211
	v_and_b32_e32 v161, 0xffff0000, v211
	v_pk_fma_f32 v[36:37], v[36:37], v[154:155], v[138:139]
	v_pk_fma_f32 v[38:39], v[38:39], v[156:157], v[140:141]
	v_pk_fma_f32 v[32:33], v[32:33], v[158:159], v[144:145]
	v_pk_fma_f32 v[34:35], v[34:35], v[160:161], v[146:147]
	v_cvt_pk_bf16_f32 v36, v36, v37
	v_cvt_pk_bf16_f32 v37, v38, v39
	v_cvt_pk_bf16_f32 v38, v32, v33
	v_cvt_pk_bf16_f32 v39, v34, v35
	global_store_dwordx4 v239, v[36:39], s[96:97] offset:256
	v_pk_add_f32 v[28:29], v[28:29], v[212:213]
	v_pk_add_f32 v[30:31], v[30:31], v[214:215]
	v_pk_add_f32 v[24:25], v[24:25], v[216:217]
	v_pk_add_f32 v[26:27], v[26:27], v[218:219]
	v_pk_mul_f32 v[28:29], v[28:29], v[246:247]
	v_pk_mul_f32 v[30:31], v[30:31], v[246:247]
	v_pk_mul_f32 v[24:25], v[24:25], v[246:247]
	v_pk_mul_f32 v[26:27], v[26:27], v[246:247]
	v_exp_f32_e32 v24, v24
	v_exp_f32_e32 v25, v25
	v_exp_f32_e32 v26, v26
	v_exp_f32_e32 v27, v27
	v_exp_f32_e32 v28, v28
	v_exp_f32_e32 v29, v29
	v_exp_f32_e32 v30, v30
	v_exp_f32_e32 v31, v31
	v_pk_add_f32 v[28:29], v[28:29], v[236:237]
	v_pk_add_f32 v[30:31], v[30:31], v[236:237]
	v_pk_add_f32 v[24:25], v[24:25], v[236:237]
	v_pk_add_f32 v[26:27], v[26:27], v[236:237]
	v_rcp_f32_e32 v24, v24
	v_rcp_f32_e32 v25, v25
	v_rcp_f32_e32 v26, v26
	v_rcp_f32_e32 v27, v27
	v_rcp_f32_e32 v28, v28
	v_rcp_f32_e32 v29, v29
	v_rcp_f32_e32 v30, v30
	v_rcp_f32_e32 v31, v31
	s_waitcnt vmcnt(12)
	v_lshlrev_b32_e32 v138, 16, v228
	v_and_b32_e32 v139, 0xffff0000, v228
	v_lshlrev_b32_e32 v140, 16, v229
	v_and_b32_e32 v141, 0xffff0000, v229
	v_lshlrev_b32_e32 v144, 16, v230
	v_and_b32_e32 v145, 0xffff0000, v230
	v_lshlrev_b32_e32 v146, 16, v231
	v_and_b32_e32 v147, 0xffff0000, v231
	v_lshlrev_b32_e32 v154, 16, v232
	v_and_b32_e32 v155, 0xffff0000, v232
	v_lshlrev_b32_e32 v156, 16, v233
	v_and_b32_e32 v157, 0xffff0000, v233
	v_lshlrev_b32_e32 v158, 16, v234
	v_and_b32_e32 v159, 0xffff0000, v234
	v_lshlrev_b32_e32 v160, 16, v235
	v_and_b32_e32 v161, 0xffff0000, v235
	v_pk_fma_f32 v[28:29], v[28:29], v[154:155], v[138:139]
	v_pk_fma_f32 v[30:31], v[30:31], v[156:157], v[140:141]
	v_pk_fma_f32 v[24:25], v[24:25], v[158:159], v[144:145]
	v_pk_fma_f32 v[26:27], v[26:27], v[160:161], v[146:147]
	v_add_u32_e32 v169, 0x50000, v245
	v_cvt_pk_bf16_f32 v28, v28, v29
	v_cvt_pk_bf16_f32 v29, v30, v31
	v_cvt_pk_bf16_f32 v30, v24, v25
	v_cvt_pk_bf16_f32 v31, v26, v27
	global_store_dwordx4 v169, v[28:31], s[96:97]
	v_pk_add_f32 v[20:21], v[20:21], v[220:221]
	v_pk_add_f32 v[22:23], v[22:23], v[222:223]
	v_pk_add_f32 v[16:17], v[16:17], v[224:225]
	v_pk_add_f32 v[18:19], v[18:19], v[226:227]
	v_pk_mul_f32 v[20:21], v[20:21], v[246:247]
	v_pk_mul_f32 v[22:23], v[22:23], v[246:247]
	v_pk_mul_f32 v[16:17], v[16:17], v[246:247]
	v_pk_mul_f32 v[18:19], v[18:19], v[246:247]
	v_exp_f32_e32 v16, v16
	v_exp_f32_e32 v17, v17
	v_exp_f32_e32 v18, v18
	v_exp_f32_e32 v19, v19
	v_exp_f32_e32 v20, v20
	v_exp_f32_e32 v21, v21
	v_exp_f32_e32 v22, v22
	v_exp_f32_e32 v23, v23
	v_pk_add_f32 v[20:21], v[20:21], v[236:237]
	v_pk_add_f32 v[22:23], v[22:23], v[236:237]
	v_pk_add_f32 v[16:17], v[16:17], v[236:237]
	v_pk_add_f32 v[18:19], v[18:19], v[236:237]
	v_rcp_f32_e32 v16, v16
	v_rcp_f32_e32 v17, v17
	v_rcp_f32_e32 v18, v18
	v_rcp_f32_e32 v19, v19
	v_rcp_f32_e32 v20, v20
	v_rcp_f32_e32 v21, v21
	v_rcp_f32_e32 v22, v22
	v_rcp_f32_e32 v23, v23
	s_waitcnt vmcnt(10)
; DI int otid() { int t = threadIdx.x; asm volatile("" : "+v"(t)); return t; }
; DI float bflo(unsigned w) { return __uint_as_float(w << 16); }
; DI float bfhi(unsigned w) { return __uint_as_float(w & 0xffff0000u); }
; DI unsigned cvt_pk_bf16(float lo, float hi) { unsigned r; asm volatile("v_cvt_pk_bf16_f32 %0, %1, %2" : "=v"(r) : "v"(lo), "v"(hi)); return r; }
; #define PG8_BAR __builtin_amdgcn_s_barrier()
; template <class Epi, bool ALIGN_EPI = true, bool SP2 = true>
; DI void gemm_phase(LAS unsigned char* lds, const Gemm g, const StaticOrder& S, const Epi& E) {
;     ...
;         { const int t2 = otid(), l2 = t2 & 63; E(acc, cur, wr, (t2 >> 6) & 3, l2 & 15, l2 >> 4); }
;         if (!has_next) break;
; #pragma unroll
;         for (int a = 0; a < 2; ++a)
; #pragma unroll
;             for (int b = 0; b < 2; ++b)
; #pragma unroll
;                 for (int m = 0; m < 4; ++m)
; #pragma unroll
;                     for (int n = 0; n < 2; ++n) acc[a][b][m][n] = (f32x4){0.f, 0.f, 0.f, 0.f};
;         cur = nxt; cA = nA; cB = nB; ++ui;
;         if constexpr (ALIGN_EPI) { if (wr == 1) PG8_BAR; }
;     }
;     DI void operator()(const f32x4 (&acc)[2][2][4][2], const pg8::Unit& u, int wr, int wc, int fr, int fq) const {
;     ...
;                     const size_t o = off + bj * 128;
;                     const f32x4 b0 = *(const f32x4*)(bg + col0 + bj * 128), b1 = *(const f32x4*)(bg + col0 + bj * 128 + 4);
;                     const u32x4 rb = *(const u32x4*)(xb + o);
;                     const u32x4 pb = *(const u32x4*)(pp + o);
;                     const f32x4 x0 = (f32x4){bflo(rb.x), bfhi(rb.x), bflo(rb.y), bfhi(rb.y)}, x1 = (f32x4){bflo(rb.z), bfhi(rb.z), bflo(rb.w), bfhi(rb.w)};
;                     const f32x4 p0 = (f32x4){bflo(pb.x), bfhi(pb.x), bflo(pb.y), bfhi(pb.y)}, p1 = (f32x4){bflo(pb.z), bfhi(pb.z), bflo(pb.w), bfhi(pb.w)};
;                     f32x4 v0, v1;
; #pragma unroll
;                     for (int j = 0; j < 4; ++j) { v0[j] = x0[j] + sigmoidf_(acc[ai][bj][m][0][j] + b0[j]) * p0[j]; v1[j] = x1[j] + sigmoidf_(acc[ai][bj][m][1][j] + b1[j]) * p1[j]; }
;                     if (out) { *(f32x4*)(out + o) = v0; *(f32x4*)(out + o + 4) = v1; }
;                     if (xbn) { u32x4 w; w.x = cvt_pk_bf16(v0[0], v0[1]); w.y = cvt_pk_bf16(v0[2], v0[3]); w.z = cvt_pk_bf16(v1[0], v1[1]); w.w = cvt_pk_bf16(v1[2], v1[3]); *(u32x4*)(xbn + o) = w; }
	v_lshlrev_b32_e32 v138, 16, v128
	v_and_b32_e32 v139, 0xffff0000, v128
	v_lshlrev_b32_e32 v140, 16, v129
	v_and_b32_e32 v141, 0xffff0000, v129
	v_lshlrev_b32_e32 v144, 16, v130
	v_and_b32_e32 v145, 0xffff0000, v130
	v_lshlrev_b32_e32 v146, 16, v131
	v_and_b32_e32 v147, 0xffff0000, v131
	v_lshlrev_b32_e32 v154, 16, v132
	v_and_b32_e32 v155, 0xffff0000, v132
	v_lshlrev_b32_e32 v156, 16, v133
	v_and_b32_e32 v157, 0xffff0000, v133
	v_lshlrev_b32_e32 v158, 16, v134
	v_and_b32_e32 v159, 0xffff0000, v134
	v_lshlrev_b32_e32 v160, 16, v135
	v_and_b32_e32 v161, 0xffff0000, v135
	v_pk_fma_f32 v[20:21], v[20:21], v[154:155], v[138:139]
	v_pk_fma_f32 v[22:23], v[22:23], v[156:157], v[140:141]
	v_pk_fma_f32 v[16:17], v[16:17], v[158:159], v[144:145]
	v_pk_fma_f32 v[18:19], v[18:19], v[160:161], v[146:147]
	v_cvt_pk_bf16_f32 v20, v20, v21
	v_cvt_pk_bf16_f32 v21, v22, v23
	v_cvt_pk_bf16_f32 v22, v16, v17
	v_cvt_pk_bf16_f32 v23, v18, v19
	global_store_dwordx4 v169, v[20:23], s[96:97] offset:256
	v_pk_add_f32 v[12:13], v[12:13], v[212:213]
	v_pk_add_f32 v[14:15], v[14:15], v[214:215]
	v_pk_add_f32 v[8:9], v[8:9], v[216:217]
	v_pk_add_f32 v[10:11], v[10:11], v[218:219]
	v_pk_mul_f32 v[12:13], v[12:13], v[246:247]
	v_pk_mul_f32 v[14:15], v[14:15], v[246:247]
	v_pk_mul_f32 v[8:9], v[8:9], v[246:247]
	v_pk_mul_f32 v[10:11], v[10:11], v[246:247]
	v_exp_f32_e32 v8, v8
	v_exp_f32_e32 v9, v9
	v_exp_f32_e32 v10, v10
	v_exp_f32_e32 v11, v11
	v_exp_f32_e32 v12, v12
	v_exp_f32_e32 v13, v13
	v_exp_f32_e32 v14, v14
	v_exp_f32_e32 v15, v15
	v_pk_add_f32 v[12:13], v[12:13], v[236:237]
	v_pk_add_f32 v[14:15], v[14:15], v[236:237]
	v_pk_add_f32 v[8:9], v[8:9], v[236:237]
	v_pk_add_f32 v[10:11], v[10:11], v[236:237]
	v_rcp_f32_e32 v8, v8
	v_rcp_f32_e32 v9, v9
	v_rcp_f32_e32 v10, v10
	v_rcp_f32_e32 v11, v11
	v_rcp_f32_e32 v12, v12
	v_rcp_f32_e32 v13, v13
	v_rcp_f32_e32 v14, v14
	v_rcp_f32_e32 v15, v15
	s_waitcnt vmcnt(8)
	v_lshlrev_b32_e32 v138, 16, v172
	v_and_b32_e32 v139, 0xffff0000, v172
	v_lshlrev_b32_e32 v140, 16, v173
	v_and_b32_e32 v141, 0xffff0000, v173
	v_lshlrev_b32_e32 v144, 16, v174
	v_and_b32_e32 v145, 0xffff0000, v174
	v_lshlrev_b32_e32 v146, 16, v175
	v_and_b32_e32 v147, 0xffff0000, v175
	v_lshlrev_b32_e32 v154, 16, v176
	v_and_b32_e32 v155, 0xffff0000, v176
	v_lshlrev_b32_e32 v156, 16, v177
	v_and_b32_e32 v157, 0xffff0000, v177
	v_lshlrev_b32_e32 v158, 16, v178
	v_and_b32_e32 v159, 0xffff0000, v178
	v_lshlrev_b32_e32 v160, 16, v179
	v_and_b32_e32 v161, 0xffff0000, v179
	v_pk_fma_f32 v[12:13], v[12:13], v[154:155], v[138:139]
	v_pk_fma_f32 v[14:15], v[14:15], v[156:157], v[140:141]
	v_pk_fma_f32 v[8:9], v[8:9], v[158:159], v[144:145]
	v_pk_fma_f32 v[10:11], v[10:11], v[160:161], v[146:147]
	v_add_u32_e32 v239, 0x58000, v245
	v_cvt_pk_bf16_f32 v12, v12, v13
	v_cvt_pk_bf16_f32 v13, v14, v15
	v_cvt_pk_bf16_f32 v14, v8, v9
	v_cvt_pk_bf16_f32 v15, v10, v11
	global_store_dwordx4 v239, v[12:15], s[96:97]
	v_pk_add_f32 v[4:5], v[4:5], v[220:221]
	v_pk_add_f32 v[6:7], v[6:7], v[222:223]
	v_pk_add_f32 v[0:1], v[0:1], v[224:225]
	v_pk_add_f32 v[2:3], v[2:3], v[226:227]
	v_pk_mul_f32 v[4:5], v[4:5], v[246:247]
	v_pk_mul_f32 v[6:7], v[6:7], v[246:247]
	v_pk_mul_f32 v[0:1], v[0:1], v[246:247]
	v_pk_mul_f32 v[2:3], v[2:3], v[246:247]
	v_exp_f32_e32 v0, v0
	v_exp_f32_e32 v1, v1
	v_exp_f32_e32 v2, v2
	v_exp_f32_e32 v3, v3
	v_exp_f32_e32 v4, v4
	v_exp_f32_e32 v5, v5
	v_exp_f32_e32 v6, v6
	v_exp_f32_e32 v7, v7
	v_pk_add_f32 v[4:5], v[4:5], v[236:237]
	v_pk_add_f32 v[6:7], v[6:7], v[236:237]
	v_pk_add_f32 v[0:1], v[0:1], v[236:237]
	v_pk_add_f32 v[2:3], v[2:3], v[236:237]
	v_rcp_f32_e32 v0, v0
	v_rcp_f32_e32 v1, v1
	v_rcp_f32_e32 v2, v2
	v_rcp_f32_e32 v3, v3
	v_rcp_f32_e32 v4, v4
	v_rcp_f32_e32 v5, v5
	v_rcp_f32_e32 v6, v6
	v_rcp_f32_e32 v7, v7
	s_waitcnt vmcnt(6)
	v_lshlrev_b32_e32 v138, 16, v180
	v_and_b32_e32 v139, 0xffff0000, v180
	v_lshlrev_b32_e32 v140, 16, v181
	v_and_b32_e32 v141, 0xffff0000, v181
	v_lshlrev_b32_e32 v144, 16, v182
	v_and_b32_e32 v145, 0xffff0000, v182
	v_lshlrev_b32_e32 v146, 16, v183
	v_and_b32_e32 v147, 0xffff0000, v183
	v_lshlrev_b32_e32 v154, 16, v184
	v_and_b32_e32 v155, 0xffff0000, v184
	v_lshlrev_b32_e32 v156, 16, v185
	v_and_b32_e32 v157, 0xffff0000, v185
	v_lshlrev_b32_e32 v158, 16, v186
	v_and_b32_e32 v159, 0xffff0000, v186
	v_lshlrev_b32_e32 v160, 16, v187
	v_and_b32_e32 v161, 0xffff0000, v187
	v_pk_fma_f32 v[4:5], v[4:5], v[154:155], v[138:139]
	v_pk_fma_f32 v[6:7], v[6:7], v[156:157], v[140:141]
	v_pk_fma_f32 v[0:1], v[0:1], v[158:159], v[144:145]
	v_pk_fma_f32 v[2:3], v[2:3], v[160:161], v[146:147]
	v_cvt_pk_bf16_f32 v4, v4, v5
	v_cvt_pk_bf16_f32 v5, v6, v7
	v_cvt_pk_bf16_f32 v6, v0, v1
	v_cvt_pk_bf16_f32 v7, v2, v3
	global_store_dwordx4 v239, v[4:7], s[96:97] offset:256
.Lepp_done:
.LBB0_658:
	s_andn2_b64 vcc, exec, s[2:3]
	s_mov_b64 s[2:3], -1
	s_cbranch_vccnz .LBB0_583
	s_andn2_b64 vcc, exec, s[74:75]
	s_cbranch_vccnz .LBB0_582
	s_barrier
	s_branch .LBB0_582
